# K-loop load segments: m0 write moved ahead of the address VALU so the s_nop 0 before each LDS-DMA goes away
# baseline (speedup 1.0000x reference)
; #define PG8_STAGE(bufoff, gbase, voff) do { _Pragma("unroll") for (int _i = 0; _i < 2; ++_i) \
;         __builtin_amdgcn_global_load_lds((const unsigned*)((const char*)(gbase) + (voff)[_i]), (PG8_LAS unsigned*)(lds + (bufoff) + ldsw + _i * 8192), 16, 0, 0); } while (0)
; #define PG8_LDA(dst, b, h) do { _Pragma("unroll") for (int m = 0; m < 4; ++m) _Pragma("unroll") for (int k = 0; k < 2; ++k) dst[m][k] = *(const PG8_LAS bf16x8*)(lds + PG8_SA(b, h) + aoff + m * 2048 + k * 1024); } while (0)
; #define PG8_LDB(dst, b, h) do { _Pragma("unroll") for (int n = 0; n < 2; ++n) _Pragma("unroll") for (int k = 0; k < 2; ++k) dst[n][k] = *(const PG8_LAS bf16x8*)(lds + PG8_SB(b, h) + boff + n * 2048 + k * 1024); } while (0)
; #define PG8_MMA(ai, bj, At, Bt) do { __builtin_amdgcn_s_setprio(1); _Pragma("unroll") for (int m = 0; m < 4; ++m) _Pragma("unroll") for (int n = 0; n < 2; ++n) _Pragma("unroll") for (int k = 0; k < 2; ++k) \
;         acc[ai][bj][m][n] = __builtin_amdgcn_mfma_f32_16x16x32_bf16(Bt[n][k], At[m][k], acc[ai][bj][m][n], 0, 0, 0); __builtin_amdgcn_s_setprio(0); } while (0)
; #define PG8_WAIT_V(n) asm volatile("s_waitcnt vmcnt(" #n ")" ::: "memory")
; #define PG8_WAIT_L(n) asm volatile("s_waitcnt lgkmcnt(" #n ")" ::: "memory")
; #define PG8_BAR __builtin_amdgcn_s_barrier()
; #define PG8_SCHED __builtin_amdgcn_sched_barrier(0)
; template <class Epi, class Sched, bool ALIGN_EPI = false, bool SP2 = false, bool KSEG = false>
; __device__ __forceinline__ void gemm_phase(PG8_LAS unsigned char* lds, const Gemm g, const Sched& S, const Epi& E) {
;     ...
;             PG8_LDB(B0, 0, 0); PG8_LDB(B1, 0, 1); PG8_SCHED; PG8_LDA(At, 0, 0); PG8_STAGE(PG8_SA(1, 1), a1 + hstep, voffA);
;             PG8_WAIT_V(8); PG8_WAIT_L(0); PG8_BAR; PG8_MMA(0, 0, At, B0); PG8_MMA(0, 1, At, B1); PG8_BAR; PG8_SCHED;
;             PG8_LDA(At, 0, 1); PG8_STAGE(PG8_SB(0, 0), b2, voffB); PG8_STAGE(PG8_SB(0, 1), b2 + hstep, voffB); PG8_STAGE(PG8_SA(0, 0), a2, voffA);
;             PG8_WAIT_V(8); PG8_WAIT_L(0); PG8_BAR; PG8_MMA(1, 0, At, B0); PG8_MMA(1, 1, At, B1); PG8_BAR; PG8_SCHED;
.LBB0_120:
	ds_read_b128 v[146:149], v156
	ds_read_b128 v[150:153], v156 offset:1024
	ds_read_b128 v[160:163], v156 offset:2048
	ds_read_b128 v[164:167], v156 offset:3072
	ds_read_b128 v[168:171], v157
	ds_read_b128 v[172:175], v157 offset:1024
	ds_read_b128 v[176:179], v157 offset:2048
	ds_read_b128 v[180:183], v157 offset:3072
	s_add_u32 s30, s28, 0xfff80080
	s_addc_u32 s31, s29, -1
	s_cmp_eq_u32 s80, 28
	s_cselect_b32 s43, s21, s31
	s_cselect_b32 s42, s64, s30
	s_cselect_b32 s31, s19, s67
	s_cselect_b32 s30, s65, s66
	s_add_u32 s98, s28, 0xfff80000
	s_addc_u32 s99, s29, -1
	s_mov_b32 m0, s51
	v_lshl_add_u64 v[216:217], s[98:99], 0, v[136:137]
	global_load_lds_dwordx4 v[216:217], off
	s_mov_b32 m0, s58
	v_lshl_add_u64 v[216:217], s[98:99], 0, v[132:133]
	global_load_lds_dwordx4 v[216:217], off
	v_lshl_add_u64 v[216:217], s[28:29], 0, v[138:139]
	s_add_i32 m0, s27, 0xc000
	ds_read_b128 v[184:187], v158
	ds_read_b128 v[188:191], v158 offset:1024
	ds_read_b128 v[192:195], v158 offset:2048
	ds_read_b128 v[196:199], v158 offset:3072
	ds_read_b128 v[200:203], v158 offset:4096
	ds_read_b128 v[204:207], v158 offset:5120
	ds_read_b128 v[208:211], v158 offset:6144
	ds_read_b128 v[212:215], v158 offset:7168
	global_load_lds_dwordx4 v[216:217], off
	s_add_i32 m0, s27, 0xe000
	v_lshl_add_u64 v[216:217], s[28:29], 0, v[140:141]
	global_load_lds_dwordx4 v[216:217], off
	s_waitcnt vmcnt(8)
	s_waitcnt lgkmcnt(0)
	s_barrier
	s_setprio 1
	s_waitcnt lgkmcnt(0)
	v_mfma_f32_16x16x32_bf16 v[126:129], v[146:149], v[184:187], v[126:129]
	v_mfma_f32_16x16x32_bf16 v[122:125], v[160:163], v[184:187], v[122:125]
	v_mfma_f32_16x16x32_bf16 v[110:113], v[146:149], v[192:195], v[110:113]
	v_mfma_f32_16x16x32_bf16 v[106:109], v[160:163], v[192:195], v[106:109]
	v_mfma_f32_16x16x32_bf16 v[94:97], v[146:149], v[200:203], v[94:97]
	v_mfma_f32_16x16x32_bf16 v[90:93], v[160:163], v[200:203], v[90:93]
	v_mfma_f32_16x16x32_bf16 v[78:81], v[146:149], v[208:211], v[78:81]
	v_mfma_f32_16x16x32_bf16 v[74:77], v[160:163], v[208:211], v[74:77]
	v_mfma_f32_16x16x32_bf16 v[126:129], v[150:153], v[188:191], v[126:129]
	v_mfma_f32_16x16x32_bf16 v[122:125], v[164:167], v[188:191], v[122:125]
	v_mfma_f32_16x16x32_bf16 v[110:113], v[150:153], v[196:199], v[110:113]
	v_mfma_f32_16x16x32_bf16 v[106:109], v[164:167], v[196:199], v[106:109]
	v_mfma_f32_16x16x32_bf16 v[94:97], v[150:153], v[204:207], v[94:97]
	v_mfma_f32_16x16x32_bf16 v[90:93], v[164:167], v[204:207], v[90:93]
	v_mfma_f32_16x16x32_bf16 v[78:81], v[150:153], v[212:215], v[78:81]
	v_mfma_f32_16x16x32_bf16 v[74:77], v[164:167], v[212:215], v[74:77]
	s_setprio 0
	s_setprio 1
	v_mfma_f32_16x16x32_bf16 v[118:121], v[168:171], v[184:187], v[118:121]
	v_mfma_f32_16x16x32_bf16 v[114:117], v[176:179], v[184:187], v[114:117]
	v_mfma_f32_16x16x32_bf16 v[102:105], v[168:171], v[192:195], v[102:105]
	v_mfma_f32_16x16x32_bf16 v[98:101], v[176:179], v[192:195], v[98:101]
	v_mfma_f32_16x16x32_bf16 v[86:89], v[168:171], v[200:203], v[86:89]
	v_mfma_f32_16x16x32_bf16 v[82:85], v[176:179], v[200:203], v[82:85]
	v_mfma_f32_16x16x32_bf16 v[70:73], v[168:171], v[208:211], v[70:73]
	v_mfma_f32_16x16x32_bf16 v[66:69], v[176:179], v[208:211], v[66:69]
	v_mfma_f32_16x16x32_bf16 v[118:121], v[172:175], v[188:191], v[118:121]
	v_mfma_f32_16x16x32_bf16 v[114:117], v[180:183], v[188:191], v[114:117]
	v_mfma_f32_16x16x32_bf16 v[102:105], v[172:175], v[196:199], v[102:105]
	v_mfma_f32_16x16x32_bf16 v[98:101], v[180:183], v[196:199], v[98:101]
	v_mfma_f32_16x16x32_bf16 v[86:89], v[172:175], v[204:207], v[86:89]
	v_mfma_f32_16x16x32_bf16 v[82:85], v[180:183], v[204:207], v[82:85]
	v_mfma_f32_16x16x32_bf16 v[70:73], v[172:175], v[212:215], v[70:73]
	v_mfma_f32_16x16x32_bf16 v[66:69], v[180:183], v[212:215], v[66:69]
	s_setprio 0
	s_barrier
	s_add_i32 s33, s60, s44
	v_lshl_add_u64 v[216:217], s[30:31], 0, v[134:135]
	s_mov_b32 m0, s33
	ds_read_b128 v[184:187], v158 offset:16384
	ds_read_b128 v[188:191], v158 offset:17408
	ds_read_b128 v[192:195], v158 offset:18432
	ds_read_b128 v[196:199], v158 offset:19456
	ds_read_b128 v[200:203], v158 offset:20480
	ds_read_b128 v[204:207], v158 offset:21504
	ds_read_b128 v[208:211], v158 offset:22528
	ds_read_b128 v[212:215], v158 offset:23552
	global_load_lds_dwordx4 v[216:217], off
	s_add_i32 m0, s33, 0x2000
	s_add_u32 s84, s30, 0x80000
	v_lshl_add_u64 v[218:219], s[30:31], 0, v[130:131]
	s_addc_u32 s85, s31, 0
	s_add_i32 s33, s61, s44
	global_load_lds_dwordx4 v[218:219], off
	s_mov_b32 m0, s33
	v_lshl_add_u64 v[220:221], s[84:85], 0, v[134:135]
	global_load_lds_dwordx4 v[220:221], off
	s_add_i32 m0, s33, 0x2000
	v_lshl_add_u64 v[220:221], s[84:85], 0, v[130:131]
	global_load_lds_dwordx4 v[220:221], off
	s_waitcnt vmcnt(6)
	s_waitcnt lgkmcnt(0)
	s_barrier
; #define PG8_STAGE(bufoff, gbase, voff) do { _Pragma("unroll") for (int _i = 0; _i < 2; ++_i) \
;         __builtin_amdgcn_global_load_lds((const unsigned*)((const char*)(gbase) + (voff)[_i]), (PG8_LAS unsigned*)(lds + (bufoff) + ldsw + _i * 8192), 16, 0, 0); } while (0)
; #define PG8_LDA(dst, b, h) do { _Pragma("unroll") for (int m = 0; m < 4; ++m) _Pragma("unroll") for (int k = 0; k < 2; ++k) dst[m][k] = *(const PG8_LAS bf16x8*)(lds + PG8_SA(b, h) + aoff + m * 2048 + k * 1024); } while (0)
; #define PG8_LDB(dst, b, h) do { _Pragma("unroll") for (int n = 0; n < 2; ++n) _Pragma("unroll") for (int k = 0; k < 2; ++k) dst[n][k] = *(const PG8_LAS bf16x8*)(lds + PG8_SB(b, h) + boff + n * 2048 + k * 1024); } while (0)
; #define PG8_MMA(ai, bj, At, Bt) do { __builtin_amdgcn_s_setprio(1); _Pragma("unroll") for (int m = 0; m < 4; ++m) _Pragma("unroll") for (int n = 0; n < 2; ++n) _Pragma("unroll") for (int k = 0; k < 2; ++k) \
;         acc[ai][bj][m][n] = __builtin_amdgcn_mfma_f32_16x16x32_bf16(Bt[n][k], At[m][k], acc[ai][bj][m][n], 0, 0, 0); __builtin_amdgcn_s_setprio(0); } while (0)
; #define PG8_WAIT_V(n) asm volatile("s_waitcnt vmcnt(" #n ")" ::: "memory")
; #define PG8_WAIT_L(n) asm volatile("s_waitcnt lgkmcnt(" #n ")" ::: "memory")
; #define PG8_BAR __builtin_amdgcn_s_barrier()
; #define PG8_SCHED __builtin_amdgcn_sched_barrier(0)
; template <class Epi, class Sched, bool ALIGN_EPI = false, bool SP2 = false, bool KSEG = false>
; __device__ __forceinline__ void gemm_phase(PG8_LAS unsigned char* lds, const Gemm g, const Sched& S, const Epi& E) {
;     ...
;             PG8_WAIT_V(8); PG8_WAIT_L(0); PG8_BAR; PG8_MMA(1, 0, At, B0); PG8_MMA(1, 1, At, B1); PG8_BAR; PG8_SCHED;
;             PG8_LDB(B0, 1, 0); PG8_LDB(B1, 1, 1); PG8_SCHED; PG8_LDA(At, 1, 0); PG8_STAGE(PG8_SA(0, 1), a2 + hstep, voffA);
;             PG8_WAIT_V(8); PG8_WAIT_L(0); PG8_BAR; PG8_MMA(0, 0, At, B0); PG8_MMA(0, 1, At, B1); PG8_BAR; PG8_SCHED;
	s_setprio 1
	s_waitcnt lgkmcnt(0)
	v_mfma_f32_16x16x32_bf16 v[62:65], v[146:149], v[184:187], v[62:65]
	v_mfma_f32_16x16x32_bf16 v[58:61], v[160:163], v[184:187], v[58:61]
	v_mfma_f32_16x16x32_bf16 v[46:49], v[146:149], v[192:195], v[46:49]
	v_mfma_f32_16x16x32_bf16 v[42:45], v[160:163], v[192:195], v[42:45]
	v_mfma_f32_16x16x32_bf16 v[30:33], v[146:149], v[200:203], v[30:33]
	v_mfma_f32_16x16x32_bf16 v[26:29], v[160:163], v[200:203], v[26:29]
	v_mfma_f32_16x16x32_bf16 v[14:17], v[146:149], v[208:211], v[14:17]
	v_mfma_f32_16x16x32_bf16 v[10:13], v[160:163], v[208:211], v[10:13]
	v_mfma_f32_16x16x32_bf16 v[62:65], v[150:153], v[188:191], v[62:65]
	v_mfma_f32_16x16x32_bf16 v[58:61], v[164:167], v[188:191], v[58:61]
	v_mfma_f32_16x16x32_bf16 v[46:49], v[150:153], v[196:199], v[46:49]
	v_mfma_f32_16x16x32_bf16 v[42:45], v[164:167], v[196:199], v[42:45]
	v_mfma_f32_16x16x32_bf16 v[30:33], v[150:153], v[204:207], v[30:33]
	v_mfma_f32_16x16x32_bf16 v[26:29], v[164:167], v[204:207], v[26:29]
	v_mfma_f32_16x16x32_bf16 v[14:17], v[150:153], v[212:215], v[14:17]
	v_mfma_f32_16x16x32_bf16 v[10:13], v[164:167], v[212:215], v[10:13]
	s_setprio 0
	s_setprio 1
	v_mfma_f32_16x16x32_bf16 v[54:57], v[168:171], v[184:187], v[54:57]
	v_mfma_f32_16x16x32_bf16 v[50:53], v[176:179], v[184:187], v[50:53]
	v_mfma_f32_16x16x32_bf16 v[38:41], v[168:171], v[192:195], v[38:41]
	v_mfma_f32_16x16x32_bf16 v[34:37], v[176:179], v[192:195], v[34:37]
	v_mfma_f32_16x16x32_bf16 v[22:25], v[168:171], v[200:203], v[22:25]
	v_mfma_f32_16x16x32_bf16 v[18:21], v[176:179], v[200:203], v[18:21]
	v_mfma_f32_16x16x32_bf16 v[6:9], v[168:171], v[208:211], v[6:9]
	v_mfma_f32_16x16x32_bf16 v[2:5], v[176:179], v[208:211], v[2:5]
	v_mfma_f32_16x16x32_bf16 v[54:57], v[172:175], v[188:191], v[54:57]
	v_mfma_f32_16x16x32_bf16 v[50:53], v[180:183], v[188:191], v[50:53]
	v_mfma_f32_16x16x32_bf16 v[38:41], v[172:175], v[196:199], v[38:41]
	v_mfma_f32_16x16x32_bf16 v[34:37], v[180:183], v[196:199], v[34:37]
	v_mfma_f32_16x16x32_bf16 v[22:25], v[172:175], v[204:207], v[22:25]
	v_mfma_f32_16x16x32_bf16 v[18:21], v[180:183], v[204:207], v[18:21]
	v_mfma_f32_16x16x32_bf16 v[6:9], v[172:175], v[212:215], v[6:9]
	v_mfma_f32_16x16x32_bf16 v[2:5], v[180:183], v[212:215], v[2:5]
	s_setprio 0
	s_barrier
	s_add_i32 s33, 0, 0x18000
	v_add_u32_e32 v159, s33, v154
	s_add_i32 s81, 0, 0x1c000
	ds_read_b128 v[146:149], v159
	ds_read_b128 v[150:153], v159 offset:1024
	ds_read_b128 v[160:163], v159 offset:2048
	ds_read_b128 v[164:167], v159 offset:3072
	v_add_u32_e32 v159, s81, v154
	ds_read_b128 v[168:171], v159
	ds_read_b128 v[172:175], v159 offset:1024
	ds_read_b128 v[176:179], v159 offset:2048
	ds_read_b128 v[180:183], v159 offset:3072
	s_mov_b32 m0, s27
	v_lshl_add_u64 v[224:225], s[42:43], 0, v[136:137]
	global_load_lds_dwordx4 v[224:225], off
	s_mov_b32 m0, s47
	v_lshl_add_u64 v[224:225], s[42:43], 0, v[132:133]
	global_load_lds_dwordx4 v[224:225], off
	s_add_u32 s42, s42, 0x80000
	s_addc_u32 s43, s43, 0
	s_mov_b32 m0, s48
	v_lshl_add_u64 v[224:225], s[42:43], 0, v[136:137]
	ds_read_b128 v[184:187], v158 offset:32768
	ds_read_b128 v[188:191], v158 offset:33792
	ds_read_b128 v[192:195], v158 offset:34816
	ds_read_b128 v[196:199], v158 offset:35840
	ds_read_b128 v[200:203], v158 offset:36864
	ds_read_b128 v[204:207], v158 offset:37888
	ds_read_b128 v[208:211], v158 offset:38912
	ds_read_b128 v[212:215], v158 offset:39936
	global_load_lds_dwordx4 v[224:225], off
	s_mov_b32 m0, s49
	v_lshl_add_u64 v[224:225], s[42:43], 0, v[132:133]
	global_load_lds_dwordx4 v[224:225], off
	s_waitcnt vmcnt(8)
	s_waitcnt lgkmcnt(0)
	s_barrier
; #define PG8_STAGE(bufoff, gbase, voff) do { _Pragma("unroll") for (int _i = 0; _i < 2; ++_i) \
;         __builtin_amdgcn_global_load_lds((const unsigned*)((const char*)(gbase) + (voff)[_i]), (PG8_LAS unsigned*)(lds + (bufoff) + ldsw + _i * 8192), 16, 0, 0); } while (0)
; #define PG8_LDA(dst, b, h) do { _Pragma("unroll") for (int m = 0; m < 4; ++m) _Pragma("unroll") for (int k = 0; k < 2; ++k) dst[m][k] = *(const PG8_LAS bf16x8*)(lds + PG8_SA(b, h) + aoff + m * 2048 + k * 1024); } while (0)
; #define PG8_MMA(ai, bj, At, Bt) do { __builtin_amdgcn_s_setprio(1); _Pragma("unroll") for (int m = 0; m < 4; ++m) _Pragma("unroll") for (int n = 0; n < 2; ++n) _Pragma("unroll") for (int k = 0; k < 2; ++k) \
;         acc[ai][bj][m][n] = __builtin_amdgcn_mfma_f32_16x16x32_bf16(Bt[n][k], At[m][k], acc[ai][bj][m][n], 0, 0, 0); __builtin_amdgcn_s_setprio(0); } while (0)
; #define PG8_WAIT_V(n) asm volatile("s_waitcnt vmcnt(" #n ")" ::: "memory")
; #define PG8_WAIT_L(n) asm volatile("s_waitcnt lgkmcnt(" #n ")" ::: "memory")
; #define PG8_BAR __builtin_amdgcn_s_barrier()
; #define PG8_SCHED __builtin_amdgcn_sched_barrier(0)
; template <class Epi, class Sched, bool ALIGN_EPI = false, bool SP2 = false, bool KSEG = false>
; __device__ __forceinline__ void gemm_phase(PG8_LAS unsigned char* lds, const Gemm g, const Sched& S, const Epi& E) {
;     ...
;             PG8_WAIT_V(8); PG8_WAIT_L(0); PG8_BAR; PG8_MMA(0, 0, At, B0); PG8_MMA(0, 1, At, B1); PG8_BAR; PG8_SCHED;
;             PG8_LDA(At, 1, 1); PG8_STAGE(PG8_SB(1, 0), b3, voffB); PG8_STAGE(PG8_SB(1, 1), b3 + hstep, voffB); PG8_STAGE(PG8_SA(1, 0), a3, voffA);
;             PG8_WAIT_V(8); PG8_WAIT_L(0); PG8_BAR; PG8_MMA(1, 0, At, B0); PG8_MMA(1, 1, At, B1); PG8_BAR; PG8_SCHED;
	s_setprio 1
	s_waitcnt lgkmcnt(0)
	v_mfma_f32_16x16x32_bf16 v[126:129], v[146:149], v[184:187], v[126:129]
	v_mfma_f32_16x16x32_bf16 v[122:125], v[160:163], v[184:187], v[122:125]
	v_mfma_f32_16x16x32_bf16 v[110:113], v[146:149], v[192:195], v[110:113]
	v_mfma_f32_16x16x32_bf16 v[106:109], v[160:163], v[192:195], v[106:109]
	v_mfma_f32_16x16x32_bf16 v[94:97], v[146:149], v[200:203], v[94:97]
	v_mfma_f32_16x16x32_bf16 v[90:93], v[160:163], v[200:203], v[90:93]
	v_mfma_f32_16x16x32_bf16 v[78:81], v[146:149], v[208:211], v[78:81]
	v_mfma_f32_16x16x32_bf16 v[74:77], v[160:163], v[208:211], v[74:77]
	v_mfma_f32_16x16x32_bf16 v[126:129], v[150:153], v[188:191], v[126:129]
	v_mfma_f32_16x16x32_bf16 v[122:125], v[164:167], v[188:191], v[122:125]
	v_mfma_f32_16x16x32_bf16 v[110:113], v[150:153], v[196:199], v[110:113]
	v_mfma_f32_16x16x32_bf16 v[106:109], v[164:167], v[196:199], v[106:109]
	v_mfma_f32_16x16x32_bf16 v[94:97], v[150:153], v[204:207], v[94:97]
	v_mfma_f32_16x16x32_bf16 v[90:93], v[164:167], v[204:207], v[90:93]
	v_mfma_f32_16x16x32_bf16 v[78:81], v[150:153], v[212:215], v[78:81]
	v_mfma_f32_16x16x32_bf16 v[74:77], v[164:167], v[212:215], v[74:77]
	s_setprio 0
	s_setprio 1
	v_mfma_f32_16x16x32_bf16 v[118:121], v[168:171], v[184:187], v[118:121]
	v_mfma_f32_16x16x32_bf16 v[114:117], v[176:179], v[184:187], v[114:117]
	v_mfma_f32_16x16x32_bf16 v[102:105], v[168:171], v[192:195], v[102:105]
	v_mfma_f32_16x16x32_bf16 v[98:101], v[176:179], v[192:195], v[98:101]
	v_mfma_f32_16x16x32_bf16 v[86:89], v[168:171], v[200:203], v[86:89]
	v_mfma_f32_16x16x32_bf16 v[82:85], v[176:179], v[200:203], v[82:85]
	v_mfma_f32_16x16x32_bf16 v[70:73], v[168:171], v[208:211], v[70:73]
	v_mfma_f32_16x16x32_bf16 v[66:69], v[176:179], v[208:211], v[66:69]
	v_mfma_f32_16x16x32_bf16 v[118:121], v[172:175], v[188:191], v[118:121]
	v_mfma_f32_16x16x32_bf16 v[114:117], v[180:183], v[188:191], v[114:117]
	v_mfma_f32_16x16x32_bf16 v[102:105], v[172:175], v[196:199], v[102:105]
	v_mfma_f32_16x16x32_bf16 v[98:101], v[180:183], v[196:199], v[98:101]
	v_mfma_f32_16x16x32_bf16 v[86:89], v[172:175], v[204:207], v[86:89]
	v_mfma_f32_16x16x32_bf16 v[82:85], v[180:183], v[204:207], v[82:85]
	v_mfma_f32_16x16x32_bf16 v[70:73], v[172:175], v[212:215], v[70:73]
	v_mfma_f32_16x16x32_bf16 v[66:69], v[180:183], v[212:215], v[66:69]
	s_setprio 0
	s_barrier
	s_add_i32 s33, s33, s44
	v_lshl_add_u64 v[216:217], v[216:217], 0, s[12:13]
	s_mov_b32 m0, s33
	ds_read_b128 v[184:187], v158 offset:49152
	ds_read_b128 v[188:191], v158 offset:50176
	ds_read_b128 v[192:195], v158 offset:51200
	ds_read_b128 v[196:199], v158 offset:52224
	ds_read_b128 v[200:203], v158 offset:53248
	ds_read_b128 v[204:207], v158 offset:54272
	ds_read_b128 v[208:211], v158 offset:55296
	ds_read_b128 v[212:215], v158 offset:56320
	global_load_lds_dwordx4 v[216:217], off
	s_add_i32 m0, s33, 0x2000
	s_add_u32 s30, s30, 0x80080
	v_lshl_add_u64 v[216:217], v[218:219], 0, s[12:13]
	s_addc_u32 s31, s31, 0
	s_add_i32 s33, s81, s44
	global_load_lds_dwordx4 v[216:217], off
	s_mov_b32 m0, s33
	v_lshl_add_u64 v[216:217], s[30:31], 0, v[134:135]
	global_load_lds_dwordx4 v[216:217], off
	s_add_i32 m0, s33, 0x2000
	v_lshl_add_u64 v[216:217], s[30:31], 0, v[130:131]
	global_load_lds_dwordx4 v[216:217], off
	s_waitcnt vmcnt(6)
	s_waitcnt lgkmcnt(0)
	s_barrier
	s_setprio 1
	s_waitcnt lgkmcnt(0)
	v_mfma_f32_16x16x32_bf16 v[62:65], v[146:149], v[184:187], v[62:65]
	v_mfma_f32_16x16x32_bf16 v[58:61], v[160:163], v[184:187], v[58:61]
	v_mfma_f32_16x16x32_bf16 v[46:49], v[146:149], v[192:195], v[46:49]
	v_mfma_f32_16x16x32_bf16 v[42:45], v[160:163], v[192:195], v[42:45]
	v_mfma_f32_16x16x32_bf16 v[30:33], v[146:149], v[200:203], v[30:33]
	v_mfma_f32_16x16x32_bf16 v[26:29], v[160:163], v[200:203], v[26:29]
	v_mfma_f32_16x16x32_bf16 v[14:17], v[146:149], v[208:211], v[14:17]
	v_mfma_f32_16x16x32_bf16 v[10:13], v[160:163], v[208:211], v[10:13]
	v_mfma_f32_16x16x32_bf16 v[62:65], v[150:153], v[188:191], v[62:65]
	v_mfma_f32_16x16x32_bf16 v[58:61], v[164:167], v[188:191], v[58:61]
	v_mfma_f32_16x16x32_bf16 v[46:49], v[150:153], v[196:199], v[46:49]
	v_mfma_f32_16x16x32_bf16 v[42:45], v[164:167], v[196:199], v[42:45]
	v_mfma_f32_16x16x32_bf16 v[30:33], v[150:153], v[204:207], v[30:33]
	v_mfma_f32_16x16x32_bf16 v[26:29], v[164:167], v[204:207], v[26:29]
	v_mfma_f32_16x16x32_bf16 v[14:17], v[150:153], v[212:215], v[14:17]
	v_mfma_f32_16x16x32_bf16 v[10:13], v[164:167], v[212:215], v[10:13]
	s_setprio 0
	s_setprio 1
	v_mfma_f32_16x16x32_bf16 v[54:57], v[168:171], v[184:187], v[54:57]
	v_mfma_f32_16x16x32_bf16 v[50:53], v[176:179], v[184:187], v[50:53]
	v_mfma_f32_16x16x32_bf16 v[38:41], v[168:171], v[192:195], v[38:41]
	v_mfma_f32_16x16x32_bf16 v[34:37], v[176:179], v[192:195], v[34:37]
	v_mfma_f32_16x16x32_bf16 v[22:25], v[168:171], v[200:203], v[22:25]
	v_mfma_f32_16x16x32_bf16 v[18:21], v[176:179], v[200:203], v[18:21]
	v_mfma_f32_16x16x32_bf16 v[6:9], v[168:171], v[208:211], v[6:9]
	v_mfma_f32_16x16x32_bf16 v[2:5], v[176:179], v[208:211], v[2:5]
	v_mfma_f32_16x16x32_bf16 v[54:57], v[172:175], v[188:191], v[54:57]
	v_mfma_f32_16x16x32_bf16 v[50:53], v[180:183], v[188:191], v[50:53]
	v_mfma_f32_16x16x32_bf16 v[38:41], v[172:175], v[196:199], v[38:41]
	v_mfma_f32_16x16x32_bf16 v[34:37], v[180:183], v[196:199], v[34:37]
	v_mfma_f32_16x16x32_bf16 v[22:25], v[172:175], v[204:207], v[22:25]
	v_mfma_f32_16x16x32_bf16 v[18:21], v[180:183], v[204:207], v[18:21]
	v_mfma_f32_16x16x32_bf16 v[6:9], v[172:175], v[212:215], v[6:9]
	v_mfma_f32_16x16x32_bf16 v[2:5], v[180:183], v[212:215], v[2:5]
	s_setprio 0
	s_barrier
	s_add_i32 s80, s80, 2
	s_add_u32 s28, s28, 0x100
	s_addc_u32 s29, s29, 0
	s_add_u32 s66, s66, 0x100
	s_addc_u32 s67, s67, 0
	s_cmp_gt_u32 s80, 29
	s_cbranch_scc0 .LBB0_120
	s_and_b64 vcc, exec, s[16:17]
	s_cbranch_vccz .LBB0_123
	s_barrier

; #define PG8_STAGE(bufoff, gbase, voff) do { _Pragma("unroll") for (int _i = 0; _i < 2; ++_i) \
;         __builtin_amdgcn_global_load_lds((const unsigned*)((const char*)(gbase) + (voff)[_i]), (PG8_LAS unsigned*)(lds + (bufoff) + ldsw + _i * 8192), 16, 0, 0); } while (0)
; #define PG8_LDA(dst, b, h) do { _Pragma("unroll") for (int m = 0; m < 4; ++m) _Pragma("unroll") for (int k = 0; k < 2; ++k) dst[m][k] = *(const PG8_LAS bf16x8*)(lds + PG8_SA(b, h) + aoff + m * 2048 + k * 1024); } while (0)
; #define PG8_LDB(dst, b, h) do { _Pragma("unroll") for (int n = 0; n < 2; ++n) _Pragma("unroll") for (int k = 0; k < 2; ++k) dst[n][k] = *(const PG8_LAS bf16x8*)(lds + PG8_SB(b, h) + boff + n * 2048 + k * 1024); } while (0)
; #define PG8_MMA(ai, bj, At, Bt) do { __builtin_amdgcn_s_setprio(1); _Pragma("unroll") for (int m = 0; m < 4; ++m) _Pragma("unroll") for (int n = 0; n < 2; ++n) _Pragma("unroll") for (int k = 0; k < 2; ++k) \
;         acc[ai][bj][m][n] = __builtin_amdgcn_mfma_f32_16x16x32_bf16(Bt[n][k], At[m][k], acc[ai][bj][m][n], 0, 0, 0); __builtin_amdgcn_s_setprio(0); } while (0)
; #define PG8_WAIT_V(n) asm volatile("s_waitcnt vmcnt(" #n ")" ::: "memory")
; #define PG8_WAIT_L(n) asm volatile("s_waitcnt lgkmcnt(" #n ")" ::: "memory")
; #define PG8_BAR __builtin_amdgcn_s_barrier()
; #define PG8_SCHED __builtin_amdgcn_sched_barrier(0)
; template <class Epi, class Sched, bool ALIGN_EPI = false, bool SP2 = false, bool KSEG = false>
; __device__ __forceinline__ void gemm_phase(PG8_LAS unsigned char* lds, const Gemm g, const Sched& S, const Epi& E) {
;     ...
;             PG8_LDB(B0, 0, 0); PG8_LDB(B1, 0, 1); PG8_SCHED; PG8_LDA(At, 0, 0); PG8_STAGE(PG8_SA(1, 1), a1 + hstep, voffA);
;             PG8_WAIT_V(8); PG8_WAIT_L(0); PG8_BAR; PG8_MMA(0, 0, At, B0); PG8_MMA(0, 1, At, B1); PG8_BAR; PG8_SCHED;
;             PG8_LDA(At, 0, 1); PG8_STAGE(PG8_SB(0, 0), b2, voffB); PG8_STAGE(PG8_SB(0, 1), b2 + hstep, voffB); PG8_STAGE(PG8_SA(0, 0), a2, voffA);
;             PG8_WAIT_V(8); PG8_WAIT_L(0); PG8_BAR; PG8_MMA(1, 0, At, B0); PG8_MMA(1, 1, At, B1); PG8_BAR; PG8_SCHED;
.LBB0_413:
	ds_read_b128 v[170:173], v160
	ds_read_b128 v[174:177], v160 offset:1024
	ds_read_b128 v[178:181], v160 offset:2048
	ds_read_b128 v[182:185], v160 offset:3072
	ds_read_b128 v[186:189], v161
	ds_read_b128 v[190:193], v161 offset:1024
	ds_read_b128 v[194:197], v161 offset:2048
	ds_read_b128 v[198:201], v161 offset:3072
	s_add_u32 s33, s40, s42
	s_addc_u32 s44, s41, s43
	s_add_u32 s33, s33, 0x100
	s_addc_u32 s44, s44, 0
	s_add_u32 s88, s85, s42
	s_addc_u32 s45, s86, s43
	s_cmpk_eq_i32 s42, 0xf00
	s_cselect_b32 s47, s23, s44
	s_cselect_b32 s46, s29, s33
	s_cselect_b32 s45, s21, s45
	s_cselect_b32 s44, s31, s88
	v_lshl_add_u64 v[4:5], v[150:151], 0, s[42:43]
	s_add_i32 m0, s51, 0xc000
	ds_read_b128 v[202:205], v162
	ds_read_b128 v[206:209], v162 offset:1024
	ds_read_b128 v[210:213], v162 offset:2048
	ds_read_b128 v[214:217], v162 offset:3072
	ds_read_b128 v[218:221], v162 offset:4096
	ds_read_b128 v[222:225], v162 offset:5120
	ds_read_b128 v[226:229], v162 offset:6144
	ds_read_b128 v[230:233], v162 offset:7168
	global_load_lds_dwordx4 v[4:5], off
	s_add_i32 m0, s51, 0xe000
	v_lshl_add_u64 v[4:5], v[152:153], 0, s[42:43]
	global_load_lds_dwordx4 v[4:5], off
	s_waitcnt vmcnt(8)
	s_waitcnt lgkmcnt(0)
	s_barrier
	s_setprio 1
	s_waitcnt lgkmcnt(0)
	v_mfma_f32_16x16x32_bf16 v[130:133], v[170:173], v[202:205], v[130:133]
	v_mfma_f32_16x16x32_bf16 v[126:129], v[178:181], v[202:205], v[126:129]
	v_mfma_f32_16x16x32_bf16 v[114:117], v[170:173], v[210:213], v[114:117]
	v_mfma_f32_16x16x32_bf16 v[110:113], v[178:181], v[210:213], v[110:113]
	v_mfma_f32_16x16x32_bf16 v[98:101], v[170:173], v[218:221], v[98:101]
	v_mfma_f32_16x16x32_bf16 v[94:97], v[178:181], v[218:221], v[94:97]
	v_mfma_f32_16x16x32_bf16 v[82:85], v[170:173], v[226:229], v[82:85]
	v_mfma_f32_16x16x32_bf16 v[78:81], v[178:181], v[226:229], v[78:81]
	v_mfma_f32_16x16x32_bf16 v[130:133], v[174:177], v[206:209], v[130:133]
	v_mfma_f32_16x16x32_bf16 v[126:129], v[182:185], v[206:209], v[126:129]
	v_mfma_f32_16x16x32_bf16 v[114:117], v[174:177], v[214:217], v[114:117]
	v_mfma_f32_16x16x32_bf16 v[110:113], v[182:185], v[214:217], v[110:113]
	v_mfma_f32_16x16x32_bf16 v[98:101], v[174:177], v[222:225], v[98:101]
	v_mfma_f32_16x16x32_bf16 v[94:97], v[182:185], v[222:225], v[94:97]
	v_mfma_f32_16x16x32_bf16 v[82:85], v[174:177], v[230:233], v[82:85]
	v_mfma_f32_16x16x32_bf16 v[78:81], v[182:185], v[230:233], v[78:81]
	s_setprio 0
	s_setprio 1
	v_mfma_f32_16x16x32_bf16 v[122:125], v[186:189], v[202:205], v[122:125]
	v_mfma_f32_16x16x32_bf16 v[118:121], v[194:197], v[202:205], v[118:121]
	v_mfma_f32_16x16x32_bf16 v[106:109], v[186:189], v[210:213], v[106:109]
	v_mfma_f32_16x16x32_bf16 v[102:105], v[194:197], v[210:213], v[102:105]
	v_mfma_f32_16x16x32_bf16 v[90:93], v[186:189], v[218:221], v[90:93]
	v_mfma_f32_16x16x32_bf16 v[86:89], v[194:197], v[218:221], v[86:89]
	v_mfma_f32_16x16x32_bf16 v[74:77], v[186:189], v[226:229], v[74:77]
	v_mfma_f32_16x16x32_bf16 v[70:73], v[194:197], v[226:229], v[70:73]
	v_mfma_f32_16x16x32_bf16 v[122:125], v[190:193], v[206:209], v[122:125]
	v_mfma_f32_16x16x32_bf16 v[118:121], v[198:201], v[206:209], v[118:121]
	v_mfma_f32_16x16x32_bf16 v[106:109], v[190:193], v[214:217], v[106:109]
	v_mfma_f32_16x16x32_bf16 v[102:105], v[198:201], v[214:217], v[102:105]
	v_mfma_f32_16x16x32_bf16 v[90:93], v[190:193], v[222:225], v[90:93]
	v_mfma_f32_16x16x32_bf16 v[86:89], v[198:201], v[222:225], v[86:89]
	v_mfma_f32_16x16x32_bf16 v[74:77], v[190:193], v[230:233], v[74:77]
	v_mfma_f32_16x16x32_bf16 v[70:73], v[198:201], v[230:233], v[70:73]
	s_setprio 0
	s_barrier
	s_add_i32 s33, s65, s50
	v_lshl_add_u64 v[234:235], s[44:45], 0, v[136:137]
	s_mov_b32 m0, s33
	ds_read_b128 v[202:205], v162 offset:16384
	ds_read_b128 v[206:209], v162 offset:17408
	ds_read_b128 v[210:213], v162 offset:18432
	ds_read_b128 v[214:217], v162 offset:19456
	ds_read_b128 v[218:221], v162 offset:20480
	ds_read_b128 v[222:225], v162 offset:21504
	ds_read_b128 v[226:229], v162 offset:22528
	ds_read_b128 v[230:233], v162 offset:23552
	global_load_lds_dwordx4 v[234:235], off
	s_add_i32 m0, s33, 0x2000
	s_add_u32 s88, s44, 0x80000
	v_lshl_add_u64 v[236:237], s[44:45], 0, v[140:141]
	s_addc_u32 s89, s45, 0
	s_add_i32 s33, s66, s50
	global_load_lds_dwordx4 v[236:237], off
	v_lshl_add_u64 v[4:5], s[88:89], 0, v[136:137]
	s_mov_b32 m0, s33
	v_lshl_add_u64 v[238:239], s[46:47], 0, v[134:135]
	global_load_lds_dwordx4 v[4:5], off
	v_lshl_add_u64 v[4:5], s[88:89], 0, v[140:141]
	s_add_i32 m0, s33, 0x2000
	v_lshl_add_u64 v[240:241], s[46:47], 0, v[138:139]
	global_load_lds_dwordx4 v[4:5], off
	s_mov_b32 m0, s51
	s_nop 0
	global_load_lds_dwordx4 v[238:239], off
	s_mov_b32 m0, s52
	s_nop 0
	global_load_lds_dwordx4 v[240:241], off
	s_waitcnt vmcnt(8)
	s_waitcnt lgkmcnt(0)
	s_barrier
; #define PG8_STAGE(bufoff, gbase, voff) do { _Pragma("unroll") for (int _i = 0; _i < 2; ++_i) \
;         __builtin_amdgcn_global_load_lds((const unsigned*)((const char*)(gbase) + (voff)[_i]), (PG8_LAS unsigned*)(lds + (bufoff) + ldsw + _i * 8192), 16, 0, 0); } while (0)
; #define PG8_LDA(dst, b, h) do { _Pragma("unroll") for (int m = 0; m < 4; ++m) _Pragma("unroll") for (int k = 0; k < 2; ++k) dst[m][k] = *(const PG8_LAS bf16x8*)(lds + PG8_SA(b, h) + aoff + m * 2048 + k * 1024); } while (0)
; #define PG8_LDB(dst, b, h) do { _Pragma("unroll") for (int n = 0; n < 2; ++n) _Pragma("unroll") for (int k = 0; k < 2; ++k) dst[n][k] = *(const PG8_LAS bf16x8*)(lds + PG8_SB(b, h) + boff + n * 2048 + k * 1024); } while (0)
; #define PG8_MMA(ai, bj, At, Bt) do { __builtin_amdgcn_s_setprio(1); _Pragma("unroll") for (int m = 0; m < 4; ++m) _Pragma("unroll") for (int n = 0; n < 2; ++n) _Pragma("unroll") for (int k = 0; k < 2; ++k) \
;         acc[ai][bj][m][n] = __builtin_amdgcn_mfma_f32_16x16x32_bf16(Bt[n][k], At[m][k], acc[ai][bj][m][n], 0, 0, 0); __builtin_amdgcn_s_setprio(0); } while (0)
; #define PG8_WAIT_V(n) asm volatile("s_waitcnt vmcnt(" #n ")" ::: "memory")
; #define PG8_WAIT_L(n) asm volatile("s_waitcnt lgkmcnt(" #n ")" ::: "memory")
; #define PG8_BAR __builtin_amdgcn_s_barrier()
; #define PG8_SCHED __builtin_amdgcn_sched_barrier(0)
; template <class Epi, class Sched, bool ALIGN_EPI = false, bool SP2 = false, bool KSEG = false>
; __device__ __forceinline__ void gemm_phase(PG8_LAS unsigned char* lds, const Gemm g, const Sched& S, const Epi& E) {
;     ...
;             PG8_WAIT_V(8); PG8_WAIT_L(0); PG8_BAR; PG8_MMA(1, 0, At, B0); PG8_MMA(1, 1, At, B1); PG8_BAR; PG8_SCHED;
;             PG8_LDB(B0, 1, 0); PG8_LDB(B1, 1, 1); PG8_SCHED; PG8_LDA(At, 1, 0); PG8_STAGE(PG8_SA(0, 1), a2 + hstep, voffA);
;             PG8_WAIT_V(8); PG8_WAIT_L(0); PG8_BAR; PG8_MMA(0, 0, At, B0); PG8_MMA(0, 1, At, B1); PG8_BAR; PG8_SCHED;
	s_setprio 1
	s_waitcnt lgkmcnt(0)
	v_mfma_f32_16x16x32_bf16 v[66:69], v[170:173], v[202:205], v[66:69]
	v_mfma_f32_16x16x32_bf16 v[62:65], v[178:181], v[202:205], v[62:65]
	v_mfma_f32_16x16x32_bf16 v[50:53], v[170:173], v[210:213], v[50:53]
	v_mfma_f32_16x16x32_bf16 v[46:49], v[178:181], v[210:213], v[46:49]
	v_mfma_f32_16x16x32_bf16 v[34:37], v[170:173], v[218:221], v[34:37]
	v_mfma_f32_16x16x32_bf16 v[30:33], v[178:181], v[218:221], v[30:33]
	v_mfma_f32_16x16x32_bf16 v[18:21], v[170:173], v[226:229], v[18:21]
	v_mfma_f32_16x16x32_bf16 v[14:17], v[178:181], v[226:229], v[14:17]
	v_mfma_f32_16x16x32_bf16 v[66:69], v[174:177], v[206:209], v[66:69]
	v_mfma_f32_16x16x32_bf16 v[62:65], v[182:185], v[206:209], v[62:65]
	v_mfma_f32_16x16x32_bf16 v[50:53], v[174:177], v[214:217], v[50:53]
	v_mfma_f32_16x16x32_bf16 v[46:49], v[182:185], v[214:217], v[46:49]
	v_mfma_f32_16x16x32_bf16 v[34:37], v[174:177], v[222:225], v[34:37]
	v_mfma_f32_16x16x32_bf16 v[30:33], v[182:185], v[222:225], v[30:33]
	v_mfma_f32_16x16x32_bf16 v[18:21], v[174:177], v[230:233], v[18:21]
	v_mfma_f32_16x16x32_bf16 v[14:17], v[182:185], v[230:233], v[14:17]
	s_setprio 0
	s_setprio 1
	v_mfma_f32_16x16x32_bf16 v[58:61], v[186:189], v[202:205], v[58:61]
	v_mfma_f32_16x16x32_bf16 v[54:57], v[194:197], v[202:205], v[54:57]
	v_mfma_f32_16x16x32_bf16 v[42:45], v[186:189], v[210:213], v[42:45]
	v_mfma_f32_16x16x32_bf16 v[38:41], v[194:197], v[210:213], v[38:41]
	v_mfma_f32_16x16x32_bf16 v[26:29], v[186:189], v[218:221], v[26:29]
	v_mfma_f32_16x16x32_bf16 v[22:25], v[194:197], v[218:221], v[22:25]
	v_mfma_f32_16x16x32_bf16 v[10:13], v[186:189], v[226:229], v[10:13]
	v_mfma_f32_16x16x32_bf16 v[4:7], v[194:197], v[226:229], v[6:9]
	v_mfma_f32_16x16x32_bf16 v[58:61], v[190:193], v[206:209], v[58:61]
	v_mfma_f32_16x16x32_bf16 v[54:57], v[198:201], v[206:209], v[54:57]
	v_mfma_f32_16x16x32_bf16 v[42:45], v[190:193], v[214:217], v[42:45]
	v_mfma_f32_16x16x32_bf16 v[38:41], v[198:201], v[214:217], v[38:41]
	v_mfma_f32_16x16x32_bf16 v[26:29], v[190:193], v[222:225], v[26:29]
	v_mfma_f32_16x16x32_bf16 v[22:25], v[198:201], v[222:225], v[22:25]
	v_mfma_f32_16x16x32_bf16 v[10:13], v[190:193], v[230:233], v[10:13]
	v_mfma_f32_16x16x32_bf16 v[4:7], v[198:201], v[230:233], v[4:7]
	s_setprio 0
	s_barrier
	s_add_i32 s33, 0, 0x18000
	v_add_u32_e32 v3, s33, v157
	s_add_i32 s88, 0, 0x1c000
	ds_read_b128 v[170:173], v3
	ds_read_b128 v[174:177], v3 offset:1024
	ds_read_b128 v[178:181], v3 offset:2048
	ds_read_b128 v[182:185], v3 offset:3072
	v_add_u32_e32 v3, s88, v157
	ds_read_b128 v[186:189], v3
	ds_read_b128 v[190:193], v3 offset:1024
	ds_read_b128 v[194:197], v3 offset:2048
	ds_read_b128 v[198:201], v3 offset:3072
	s_add_u32 s46, s46, 0x80000
	s_addc_u32 s47, s47, 0
	s_mov_b32 m0, s53
	v_lshl_add_u64 v[8:9], s[46:47], 0, v[134:135]
	ds_read_b128 v[202:205], v162 offset:32768
	ds_read_b128 v[206:209], v162 offset:33792
	ds_read_b128 v[210:213], v162 offset:34816
	ds_read_b128 v[214:217], v162 offset:35840
	ds_read_b128 v[218:221], v162 offset:36864
	ds_read_b128 v[222:225], v162 offset:37888
	ds_read_b128 v[226:229], v162 offset:38912
	ds_read_b128 v[230:233], v162 offset:39936
	global_load_lds_dwordx4 v[8:9], off
	s_mov_b32 m0, s54
	v_lshl_add_u64 v[8:9], s[46:47], 0, v[138:139]
	global_load_lds_dwordx4 v[8:9], off
	s_waitcnt vmcnt(8)
	s_waitcnt lgkmcnt(0)
	s_barrier
	s_setprio 1
	s_waitcnt lgkmcnt(0)
	v_mfma_f32_16x16x32_bf16 v[130:133], v[170:173], v[202:205], v[130:133]
	v_mfma_f32_16x16x32_bf16 v[126:129], v[178:181], v[202:205], v[126:129]
	v_mfma_f32_16x16x32_bf16 v[114:117], v[170:173], v[210:213], v[114:117]
	v_mfma_f32_16x16x32_bf16 v[110:113], v[178:181], v[210:213], v[110:113]
	v_mfma_f32_16x16x32_bf16 v[98:101], v[170:173], v[218:221], v[98:101]
	v_mfma_f32_16x16x32_bf16 v[94:97], v[178:181], v[218:221], v[94:97]
	v_mfma_f32_16x16x32_bf16 v[82:85], v[170:173], v[226:229], v[82:85]
	v_mfma_f32_16x16x32_bf16 v[78:81], v[178:181], v[226:229], v[78:81]
	v_mfma_f32_16x16x32_bf16 v[130:133], v[174:177], v[206:209], v[130:133]
	v_mfma_f32_16x16x32_bf16 v[126:129], v[182:185], v[206:209], v[126:129]
	v_mfma_f32_16x16x32_bf16 v[114:117], v[174:177], v[214:217], v[114:117]
	v_mfma_f32_16x16x32_bf16 v[110:113], v[182:185], v[214:217], v[110:113]
	v_mfma_f32_16x16x32_bf16 v[98:101], v[174:177], v[222:225], v[98:101]
	v_mfma_f32_16x16x32_bf16 v[94:97], v[182:185], v[222:225], v[94:97]
	v_mfma_f32_16x16x32_bf16 v[82:85], v[174:177], v[230:233], v[82:85]
	v_mfma_f32_16x16x32_bf16 v[78:81], v[182:185], v[230:233], v[78:81]
	s_setprio 0
	s_setprio 1
	v_mfma_f32_16x16x32_bf16 v[122:125], v[186:189], v[202:205], v[122:125]
	v_mfma_f32_16x16x32_bf16 v[118:121], v[194:197], v[202:205], v[118:121]
	v_mfma_f32_16x16x32_bf16 v[106:109], v[186:189], v[210:213], v[106:109]
	v_mfma_f32_16x16x32_bf16 v[102:105], v[194:197], v[210:213], v[102:105]
	v_mfma_f32_16x16x32_bf16 v[90:93], v[186:189], v[218:221], v[90:93]
	v_mfma_f32_16x16x32_bf16 v[86:89], v[194:197], v[218:221], v[86:89]
	v_mfma_f32_16x16x32_bf16 v[74:77], v[186:189], v[226:229], v[74:77]
	v_mfma_f32_16x16x32_bf16 v[70:73], v[194:197], v[226:229], v[70:73]
	v_mfma_f32_16x16x32_bf16 v[122:125], v[190:193], v[206:209], v[122:125]
	v_mfma_f32_16x16x32_bf16 v[118:121], v[198:201], v[206:209], v[118:121]
	v_mfma_f32_16x16x32_bf16 v[106:109], v[190:193], v[214:217], v[106:109]
	v_mfma_f32_16x16x32_bf16 v[102:105], v[198:201], v[214:217], v[102:105]
	v_mfma_f32_16x16x32_bf16 v[90:93], v[190:193], v[222:225], v[90:93]
	v_mfma_f32_16x16x32_bf16 v[86:89], v[198:201], v[222:225], v[86:89]
	v_mfma_f32_16x16x32_bf16 v[74:77], v[190:193], v[230:233], v[74:77]
	v_mfma_f32_16x16x32_bf16 v[70:73], v[198:201], v[230:233], v[70:73]
	s_setprio 0
	s_barrier
; #define PG8_STAGE(bufoff, gbase, voff) do { _Pragma("unroll") for (int _i = 0; _i < 2; ++_i) \
;         __builtin_amdgcn_global_load_lds((const unsigned*)((const char*)(gbase) + (voff)[_i]), (PG8_LAS unsigned*)(lds + (bufoff) + ldsw + _i * 8192), 16, 0, 0); } while (0)
; #define PG8_LDA(dst, b, h) do { _Pragma("unroll") for (int m = 0; m < 4; ++m) _Pragma("unroll") for (int k = 0; k < 2; ++k) dst[m][k] = *(const PG8_LAS bf16x8*)(lds + PG8_SA(b, h) + aoff + m * 2048 + k * 1024); } while (0)
; #define PG8_MMA(ai, bj, At, Bt) do { __builtin_amdgcn_s_setprio(1); _Pragma("unroll") for (int m = 0; m < 4; ++m) _Pragma("unroll") for (int n = 0; n < 2; ++n) _Pragma("unroll") for (int k = 0; k < 2; ++k) \
;         acc[ai][bj][m][n] = __builtin_amdgcn_mfma_f32_16x16x32_bf16(Bt[n][k], At[m][k], acc[ai][bj][m][n], 0, 0, 0); __builtin_amdgcn_s_setprio(0); } while (0)
; #define PG8_WAIT_V(n) asm volatile("s_waitcnt vmcnt(" #n ")" ::: "memory")
; #define PG8_WAIT_L(n) asm volatile("s_waitcnt lgkmcnt(" #n ")" ::: "memory")
; #define PG8_BAR __builtin_amdgcn_s_barrier()
; #define PG8_SCHED __builtin_amdgcn_sched_barrier(0)
; template <class Epi, class Sched, bool ALIGN_EPI = false, bool SP2 = false, bool KSEG = false>
; __device__ __forceinline__ void gemm_phase(PG8_LAS unsigned char* lds, const Gemm g, const Sched& S, const Epi& E) {
;     ...
;             PG8_LDA(At, 1, 1); PG8_STAGE(PG8_SB(1, 0), b3, voffB); PG8_STAGE(PG8_SB(1, 1), b3 + hstep, voffB); PG8_STAGE(PG8_SA(1, 0), a3, voffA);
;             PG8_WAIT_V(8); PG8_WAIT_L(0); PG8_BAR; PG8_MMA(1, 0, At, B0); PG8_MMA(1, 1, At, B1); PG8_BAR; PG8_SCHED;
;     ...
;             if constexpr (KSEG) { if (t == 14 || t == 22) E.kscale(acc, ui, t == 14 ? 0 : 1, wr, fr); }
	s_add_i32 s33, s33, s50
	v_lshl_add_u64 v[8:9], v[234:235], 0, s[8:9]
	s_mov_b32 m0, s33
	ds_read_b128 v[202:205], v162 offset:49152
	ds_read_b128 v[206:209], v162 offset:50176
	ds_read_b128 v[210:213], v162 offset:51200
	ds_read_b128 v[214:217], v162 offset:52224
	ds_read_b128 v[218:221], v162 offset:53248
	ds_read_b128 v[222:225], v162 offset:54272
	ds_read_b128 v[226:229], v162 offset:55296
	ds_read_b128 v[230:233], v162 offset:56320
	global_load_lds_dwordx4 v[8:9], off
	s_add_i32 m0, s33, 0x2000
	s_add_u32 s44, s44, 0x80080
	v_lshl_add_u64 v[8:9], v[236:237], 0, s[8:9]
	s_addc_u32 s45, s45, 0
	s_add_i32 s33, s88, s50
	global_load_lds_dwordx4 v[8:9], off
	s_mov_b32 m0, s33
	v_lshl_add_u64 v[8:9], s[44:45], 0, v[136:137]
	global_load_lds_dwordx4 v[8:9], off
	s_add_i32 m0, s33, 0x2000
	v_lshl_add_u64 v[8:9], s[44:45], 0, v[140:141]
	global_load_lds_dwordx4 v[8:9], off
	s_mov_b32 m0, s55
	v_lshl_add_u64 v[8:9], v[238:239], 0, s[8:9]
	global_load_lds_dwordx4 v[8:9], off
	s_mov_b32 m0, s56
	v_lshl_add_u64 v[8:9], v[240:241], 0, s[8:9]
	global_load_lds_dwordx4 v[8:9], off
	s_waitcnt vmcnt(8)
	s_waitcnt lgkmcnt(0)
	s_barrier
	s_setprio 1
	s_waitcnt lgkmcnt(0)
	v_mfma_f32_16x16x32_bf16 v[66:69], v[170:173], v[202:205], v[66:69]
	v_mfma_f32_16x16x32_bf16 v[62:65], v[178:181], v[202:205], v[62:65]
	v_mfma_f32_16x16x32_bf16 v[50:53], v[170:173], v[210:213], v[50:53]
	v_mfma_f32_16x16x32_bf16 v[46:49], v[178:181], v[210:213], v[46:49]
	v_mfma_f32_16x16x32_bf16 v[34:37], v[170:173], v[218:221], v[34:37]
	v_mfma_f32_16x16x32_bf16 v[30:33], v[178:181], v[218:221], v[30:33]
	v_mfma_f32_16x16x32_bf16 v[18:21], v[170:173], v[226:229], v[18:21]
	v_mfma_f32_16x16x32_bf16 v[14:17], v[178:181], v[226:229], v[14:17]
	v_mfma_f32_16x16x32_bf16 v[66:69], v[174:177], v[206:209], v[66:69]
	v_mfma_f32_16x16x32_bf16 v[62:65], v[182:185], v[206:209], v[62:65]
	v_mfma_f32_16x16x32_bf16 v[50:53], v[174:177], v[214:217], v[50:53]
	v_mfma_f32_16x16x32_bf16 v[46:49], v[182:185], v[214:217], v[46:49]
	v_mfma_f32_16x16x32_bf16 v[34:37], v[174:177], v[222:225], v[34:37]
	v_mfma_f32_16x16x32_bf16 v[30:33], v[182:185], v[222:225], v[30:33]
	v_mfma_f32_16x16x32_bf16 v[18:21], v[174:177], v[230:233], v[18:21]
	v_mfma_f32_16x16x32_bf16 v[14:17], v[182:185], v[230:233], v[14:17]
	s_setprio 0
	s_setprio 1
	v_mfma_f32_16x16x32_bf16 v[58:61], v[186:189], v[202:205], v[58:61]
	v_mfma_f32_16x16x32_bf16 v[54:57], v[194:197], v[202:205], v[54:57]
	v_mfma_f32_16x16x32_bf16 v[42:45], v[186:189], v[210:213], v[42:45]
	v_mfma_f32_16x16x32_bf16 v[38:41], v[194:197], v[210:213], v[38:41]
	v_mfma_f32_16x16x32_bf16 v[26:29], v[186:189], v[218:221], v[26:29]
	v_mfma_f32_16x16x32_bf16 v[22:25], v[194:197], v[218:221], v[22:25]
	v_mfma_f32_16x16x32_bf16 v[8:11], v[186:189], v[226:229], v[10:13]
	v_mfma_f32_16x16x32_bf16 v[4:7], v[194:197], v[226:229], v[4:7]
	v_mfma_f32_16x16x32_bf16 v[58:61], v[190:193], v[206:209], v[58:61]
	v_mfma_f32_16x16x32_bf16 v[54:57], v[198:201], v[206:209], v[54:57]
	v_mfma_f32_16x16x32_bf16 v[42:45], v[190:193], v[214:217], v[42:45]
	v_mfma_f32_16x16x32_bf16 v[38:41], v[198:201], v[214:217], v[38:41]
	v_mfma_f32_16x16x32_bf16 v[26:29], v[190:193], v[222:225], v[26:29]
	v_mfma_f32_16x16x32_bf16 v[22:25], v[198:201], v[222:225], v[22:25]
	v_mfma_f32_16x16x32_bf16 v[10:13], v[190:193], v[230:233], v[8:11]
	v_mfma_f32_16x16x32_bf16 v[6:9], v[198:201], v[230:233], v[4:7]
	s_setprio 0
	s_barrier
	s_cmp_lt_i32 s87, 22
	s_cbranch_scc1 .LBB0_415
	s_cmp_eq_u32 s87, 22
	s_cselect_b64 s[44:45], -1, 0
	s_cbranch_execz .LBB0_416
	s_branch .LBB0_417

; #define PG8_STAGE(bufoff, gbase, voff) do { _Pragma("unroll") for (int _i = 0; _i < 2; ++_i) \
;         __builtin_amdgcn_global_load_lds((const unsigned*)((const char*)(gbase) + (voff)[_i]), (PG8_LAS unsigned*)(lds + (bufoff) + ldsw + _i * 8192), 16, 0, 0); } while (0)
; #define PG8_LDA(dst, b, h) do { _Pragma("unroll") for (int m = 0; m < 4; ++m) _Pragma("unroll") for (int k = 0; k < 2; ++k) dst[m][k] = *(const PG8_LAS bf16x8*)(lds + PG8_SA(b, h) + aoff + m * 2048 + k * 1024); } while (0)
; #define PG8_LDB(dst, b, h) do { _Pragma("unroll") for (int n = 0; n < 2; ++n) _Pragma("unroll") for (int k = 0; k < 2; ++k) dst[n][k] = *(const PG8_LAS bf16x8*)(lds + PG8_SB(b, h) + boff + n * 2048 + k * 1024); } while (0)
; #define PG8_MMA(ai, bj, At, Bt) do { __builtin_amdgcn_s_setprio(1); _Pragma("unroll") for (int m = 0; m < 4; ++m) _Pragma("unroll") for (int n = 0; n < 2; ++n) _Pragma("unroll") for (int k = 0; k < 2; ++k) \
;         acc[ai][bj][m][n] = __builtin_amdgcn_mfma_f32_16x16x32_bf16(Bt[n][k], At[m][k], acc[ai][bj][m][n], 0, 0, 0); __builtin_amdgcn_s_setprio(0); } while (0)
; #define PG8_WAIT_V(n) asm volatile("s_waitcnt vmcnt(" #n ")" ::: "memory")
; #define PG8_WAIT_L(n) asm volatile("s_waitcnt lgkmcnt(" #n ")" ::: "memory")
; #define PG8_BAR __builtin_amdgcn_s_barrier()
; #define PG8_SCHED __builtin_amdgcn_sched_barrier(0)
; template <class Epi, class Sched, bool ALIGN_EPI = false, bool SP2 = false, bool KSEG = false>
; __device__ __forceinline__ void gemm_phase(PG8_LAS unsigned char* lds, const Gemm g, const Sched& S, const Epi& E) {
;     ...
;             PG8_LDB(B0, 0, 0); PG8_LDB(B1, 0, 1); PG8_SCHED; PG8_LDA(At, 0, 0); PG8_STAGE(PG8_SA(1, 1), a1 + hstep, voffA);
;             PG8_WAIT_V(8); PG8_WAIT_L(0); PG8_BAR; PG8_MMA(0, 0, At, B0); PG8_MMA(0, 1, At, B1); PG8_BAR; PG8_SCHED;
;             PG8_LDA(At, 0, 1); PG8_STAGE(PG8_SB(0, 0), b2, voffB); PG8_STAGE(PG8_SB(0, 1), b2 + hstep, voffB); PG8_STAGE(PG8_SA(0, 0), a2, voffA);
;             PG8_WAIT_V(8); PG8_WAIT_L(0); PG8_BAR; PG8_MMA(1, 0, At, B0); PG8_MMA(1, 1, At, B1); PG8_BAR; PG8_SCHED;
.LBB0_497:
	ds_read_b128 v[148:151], v168
	ds_read_b128 v[172:175], v168 offset:1024
	ds_read_b128 v[176:179], v168 offset:2048
	ds_read_b128 v[180:183], v168 offset:3072
	ds_read_b128 v[184:187], v169
	ds_read_b128 v[188:191], v169 offset:1024
	ds_read_b128 v[192:195], v169 offset:2048
	ds_read_b128 v[196:199], v169 offset:3072
	s_add_u32 s33, s36, 0xfff80080
	s_addc_u32 s38, s37, -1
	s_cmp_eq_u32 s62, 28
	s_cselect_b32 s41, s25, s38
	s_cselect_b32 s40, s58, s33
	s_cselect_b32 s39, s23, s61
	s_cselect_b32 s38, s59, s60
	s_add_u32 s98, s36, 0xfff80000
	s_addc_u32 s99, s37, -1
	s_mov_b32 m0, s52
	v_lshl_add_u64 v[232:233], s[98:99], 0, v[132:133]
	global_load_lds_dwordx4 v[232:233], off
	s_mov_b32 m0, s53
	v_lshl_add_u64 v[232:233], s[98:99], 0, v[136:137]
	global_load_lds_dwordx4 v[232:233], off
	v_lshl_add_u64 v[232:233], s[36:37], 0, v[140:141]
	s_add_i32 m0, s31, 0xc000
	ds_read_b128 v[200:203], v170
	ds_read_b128 v[204:207], v170 offset:1024
	ds_read_b128 v[208:211], v170 offset:2048
	ds_read_b128 v[212:215], v170 offset:3072
	ds_read_b128 v[216:219], v170 offset:4096
	ds_read_b128 v[220:223], v170 offset:5120
	ds_read_b128 v[224:227], v170 offset:6144
	ds_read_b128 v[228:231], v170 offset:7168
	global_load_lds_dwordx4 v[232:233], off
	s_add_i32 m0, s31, 0xe000
	v_lshl_add_u64 v[232:233], s[36:37], 0, v[142:143]
	global_load_lds_dwordx4 v[232:233], off
	s_waitcnt vmcnt(8)
	s_waitcnt lgkmcnt(0)
	s_barrier
	s_setprio 1
	s_waitcnt lgkmcnt(0)
	v_mfma_f32_16x16x32_bf16 v[126:129], v[148:151], v[200:203], v[126:129]
	v_mfma_f32_16x16x32_bf16 v[122:125], v[176:179], v[200:203], v[122:125]
	v_mfma_f32_16x16x32_bf16 v[110:113], v[148:151], v[208:211], v[110:113]
	v_mfma_f32_16x16x32_bf16 v[106:109], v[176:179], v[208:211], v[106:109]
	v_mfma_f32_16x16x32_bf16 v[94:97], v[148:151], v[216:219], v[94:97]
	v_mfma_f32_16x16x32_bf16 v[90:93], v[176:179], v[216:219], v[90:93]
	v_mfma_f32_16x16x32_bf16 v[78:81], v[148:151], v[224:227], v[78:81]
	v_mfma_f32_16x16x32_bf16 v[74:77], v[176:179], v[224:227], v[74:77]
	v_mfma_f32_16x16x32_bf16 v[126:129], v[172:175], v[204:207], v[126:129]
	v_mfma_f32_16x16x32_bf16 v[122:125], v[180:183], v[204:207], v[122:125]
	v_mfma_f32_16x16x32_bf16 v[110:113], v[172:175], v[212:215], v[110:113]
	v_mfma_f32_16x16x32_bf16 v[106:109], v[180:183], v[212:215], v[106:109]
	v_mfma_f32_16x16x32_bf16 v[94:97], v[172:175], v[220:223], v[94:97]
	v_mfma_f32_16x16x32_bf16 v[90:93], v[180:183], v[220:223], v[90:93]
	v_mfma_f32_16x16x32_bf16 v[78:81], v[172:175], v[228:231], v[78:81]
	v_mfma_f32_16x16x32_bf16 v[74:77], v[180:183], v[228:231], v[74:77]
	s_setprio 0
	s_setprio 1
	v_mfma_f32_16x16x32_bf16 v[118:121], v[184:187], v[200:203], v[118:121]
	v_mfma_f32_16x16x32_bf16 v[114:117], v[192:195], v[200:203], v[114:117]
	v_mfma_f32_16x16x32_bf16 v[102:105], v[184:187], v[208:211], v[102:105]
	v_mfma_f32_16x16x32_bf16 v[98:101], v[192:195], v[208:211], v[98:101]
	v_mfma_f32_16x16x32_bf16 v[86:89], v[184:187], v[216:219], v[86:89]
	v_mfma_f32_16x16x32_bf16 v[82:85], v[192:195], v[216:219], v[82:85]
	v_mfma_f32_16x16x32_bf16 v[70:73], v[184:187], v[224:227], v[70:73]
	v_mfma_f32_16x16x32_bf16 v[66:69], v[192:195], v[224:227], v[66:69]
	v_mfma_f32_16x16x32_bf16 v[118:121], v[188:191], v[204:207], v[118:121]
	v_mfma_f32_16x16x32_bf16 v[114:117], v[196:199], v[204:207], v[114:117]
	v_mfma_f32_16x16x32_bf16 v[102:105], v[188:191], v[212:215], v[102:105]
	v_mfma_f32_16x16x32_bf16 v[98:101], v[196:199], v[212:215], v[98:101]
	v_mfma_f32_16x16x32_bf16 v[86:89], v[188:191], v[220:223], v[86:89]
	v_mfma_f32_16x16x32_bf16 v[82:85], v[196:199], v[220:223], v[82:85]
	v_mfma_f32_16x16x32_bf16 v[70:73], v[188:191], v[228:231], v[70:73]
	v_mfma_f32_16x16x32_bf16 v[66:69], v[196:199], v[228:231], v[66:69]
	s_setprio 0
	s_barrier
	s_add_i32 s33, s54, s43
	v_lshl_add_u64 v[232:233], s[38:39], 0, v[134:135]
	s_mov_b32 m0, s33
	ds_read_b128 v[200:203], v170 offset:16384
	ds_read_b128 v[204:207], v170 offset:17408
	ds_read_b128 v[208:211], v170 offset:18432
	ds_read_b128 v[212:215], v170 offset:19456
	ds_read_b128 v[216:219], v170 offset:20480
	ds_read_b128 v[220:223], v170 offset:21504
	ds_read_b128 v[224:227], v170 offset:22528
	ds_read_b128 v[228:231], v170 offset:23552
	global_load_lds_dwordx4 v[232:233], off
	s_add_i32 m0, s33, 0x2000
	s_add_u32 s64, s38, 0x80000
	v_lshl_add_u64 v[234:235], s[38:39], 0, v[138:139]
	s_addc_u32 s65, s39, 0
	s_add_i32 s33, s55, s43
	global_load_lds_dwordx4 v[234:235], off
	s_mov_b32 m0, s33
	v_lshl_add_u64 v[236:237], s[64:65], 0, v[134:135]
	global_load_lds_dwordx4 v[236:237], off
	s_add_i32 m0, s33, 0x2000
	v_lshl_add_u64 v[236:237], s[64:65], 0, v[138:139]
	global_load_lds_dwordx4 v[236:237], off
	s_waitcnt vmcnt(6)
	s_waitcnt lgkmcnt(0)
	s_barrier
; #define PG8_STAGE(bufoff, gbase, voff) do { _Pragma("unroll") for (int _i = 0; _i < 2; ++_i) \
;         __builtin_amdgcn_global_load_lds((const unsigned*)((const char*)(gbase) + (voff)[_i]), (PG8_LAS unsigned*)(lds + (bufoff) + ldsw + _i * 8192), 16, 0, 0); } while (0)
; #define PG8_LDA(dst, b, h) do { _Pragma("unroll") for (int m = 0; m < 4; ++m) _Pragma("unroll") for (int k = 0; k < 2; ++k) dst[m][k] = *(const PG8_LAS bf16x8*)(lds + PG8_SA(b, h) + aoff + m * 2048 + k * 1024); } while (0)
; #define PG8_LDB(dst, b, h) do { _Pragma("unroll") for (int n = 0; n < 2; ++n) _Pragma("unroll") for (int k = 0; k < 2; ++k) dst[n][k] = *(const PG8_LAS bf16x8*)(lds + PG8_SB(b, h) + boff + n * 2048 + k * 1024); } while (0)
; #define PG8_MMA(ai, bj, At, Bt) do { __builtin_amdgcn_s_setprio(1); _Pragma("unroll") for (int m = 0; m < 4; ++m) _Pragma("unroll") for (int n = 0; n < 2; ++n) _Pragma("unroll") for (int k = 0; k < 2; ++k) \
;         acc[ai][bj][m][n] = __builtin_amdgcn_mfma_f32_16x16x32_bf16(Bt[n][k], At[m][k], acc[ai][bj][m][n], 0, 0, 0); __builtin_amdgcn_s_setprio(0); } while (0)
; #define PG8_WAIT_V(n) asm volatile("s_waitcnt vmcnt(" #n ")" ::: "memory")
; #define PG8_WAIT_L(n) asm volatile("s_waitcnt lgkmcnt(" #n ")" ::: "memory")
; #define PG8_BAR __builtin_amdgcn_s_barrier()
; #define PG8_SCHED __builtin_amdgcn_sched_barrier(0)
; template <class Epi, class Sched, bool ALIGN_EPI = false, bool SP2 = false, bool KSEG = false>
; __device__ __forceinline__ void gemm_phase(PG8_LAS unsigned char* lds, const Gemm g, const Sched& S, const Epi& E) {
;     ...
;             PG8_WAIT_V(8); PG8_WAIT_L(0); PG8_BAR; PG8_MMA(1, 0, At, B0); PG8_MMA(1, 1, At, B1); PG8_BAR; PG8_SCHED;
;             PG8_LDB(B0, 1, 0); PG8_LDB(B1, 1, 1); PG8_SCHED; PG8_LDA(At, 1, 0); PG8_STAGE(PG8_SA(0, 1), a2 + hstep, voffA);
;             PG8_WAIT_V(8); PG8_WAIT_L(0); PG8_BAR; PG8_MMA(0, 0, At, B0); PG8_MMA(0, 1, At, B1); PG8_BAR; PG8_SCHED;
	s_setprio 1
	s_waitcnt lgkmcnt(0)
	v_mfma_f32_16x16x32_bf16 v[62:65], v[148:151], v[200:203], v[62:65]
	v_mfma_f32_16x16x32_bf16 v[58:61], v[176:179], v[200:203], v[58:61]
	v_mfma_f32_16x16x32_bf16 v[46:49], v[148:151], v[208:211], v[46:49]
	v_mfma_f32_16x16x32_bf16 v[42:45], v[176:179], v[208:211], v[42:45]
	v_mfma_f32_16x16x32_bf16 v[30:33], v[148:151], v[216:219], v[30:33]
	v_mfma_f32_16x16x32_bf16 v[26:29], v[176:179], v[216:219], v[26:29]
	v_mfma_f32_16x16x32_bf16 v[14:17], v[148:151], v[224:227], v[14:17]
	v_mfma_f32_16x16x32_bf16 v[10:13], v[176:179], v[224:227], v[10:13]
	v_mfma_f32_16x16x32_bf16 v[62:65], v[172:175], v[204:207], v[62:65]
	v_mfma_f32_16x16x32_bf16 v[58:61], v[180:183], v[204:207], v[58:61]
	v_mfma_f32_16x16x32_bf16 v[46:49], v[172:175], v[212:215], v[46:49]
	v_mfma_f32_16x16x32_bf16 v[42:45], v[180:183], v[212:215], v[42:45]
	v_mfma_f32_16x16x32_bf16 v[30:33], v[172:175], v[220:223], v[30:33]
	v_mfma_f32_16x16x32_bf16 v[26:29], v[180:183], v[220:223], v[26:29]
	v_mfma_f32_16x16x32_bf16 v[14:17], v[172:175], v[228:231], v[14:17]
	v_mfma_f32_16x16x32_bf16 v[10:13], v[180:183], v[228:231], v[10:13]
	s_setprio 0
	s_setprio 1
	v_mfma_f32_16x16x32_bf16 v[54:57], v[184:187], v[200:203], v[54:57]
	v_mfma_f32_16x16x32_bf16 v[50:53], v[192:195], v[200:203], v[50:53]
	v_mfma_f32_16x16x32_bf16 v[38:41], v[184:187], v[208:211], v[38:41]
	v_mfma_f32_16x16x32_bf16 v[34:37], v[192:195], v[208:211], v[34:37]
	v_mfma_f32_16x16x32_bf16 v[22:25], v[184:187], v[216:219], v[22:25]
	v_mfma_f32_16x16x32_bf16 v[18:21], v[192:195], v[216:219], v[18:21]
	v_mfma_f32_16x16x32_bf16 v[6:9], v[184:187], v[224:227], v[6:9]
	v_mfma_f32_16x16x32_bf16 v[2:5], v[192:195], v[224:227], v[2:5]
	v_mfma_f32_16x16x32_bf16 v[54:57], v[188:191], v[204:207], v[54:57]
	v_mfma_f32_16x16x32_bf16 v[50:53], v[196:199], v[204:207], v[50:53]
	v_mfma_f32_16x16x32_bf16 v[38:41], v[188:191], v[212:215], v[38:41]
	v_mfma_f32_16x16x32_bf16 v[34:37], v[196:199], v[212:215], v[34:37]
	v_mfma_f32_16x16x32_bf16 v[22:25], v[188:191], v[220:223], v[22:25]
	v_mfma_f32_16x16x32_bf16 v[18:21], v[196:199], v[220:223], v[18:21]
	v_mfma_f32_16x16x32_bf16 v[6:9], v[188:191], v[228:231], v[6:9]
	v_mfma_f32_16x16x32_bf16 v[2:5], v[196:199], v[228:231], v[2:5]
	s_setprio 0
	s_barrier
	s_add_i32 s33, 0, 0x18000
	s_add_i32 s63, 0, 0x1c000
	v_add_u32_e32 v180, s33, v166
	v_add_u32_e32 v196, s63, v166
	ds_read_b128 v[148:151], v180
	ds_read_b128 v[172:175], v180 offset:1024
	ds_read_b128 v[176:179], v180 offset:2048
	ds_read_b128 v[180:183], v180 offset:3072
	ds_read_b128 v[184:187], v196
	ds_read_b128 v[188:191], v196 offset:1024
	ds_read_b128 v[192:195], v196 offset:2048
	ds_read_b128 v[196:199], v196 offset:3072
	s_mov_b32 m0, s31
	v_lshl_add_u64 v[240:241], s[40:41], 0, v[132:133]
	global_load_lds_dwordx4 v[240:241], off
	s_mov_b32 m0, s45
	v_lshl_add_u64 v[240:241], s[40:41], 0, v[136:137]
	global_load_lds_dwordx4 v[240:241], off
	s_add_u32 s40, s40, 0x80000
	s_addc_u32 s41, s41, 0
	s_mov_b32 m0, s49
	v_lshl_add_u64 v[240:241], s[40:41], 0, v[132:133]
	ds_read_b128 v[200:203], v170 offset:32768
	ds_read_b128 v[204:207], v170 offset:33792
	ds_read_b128 v[208:211], v170 offset:34816
	ds_read_b128 v[212:215], v170 offset:35840
	ds_read_b128 v[216:219], v170 offset:36864
	ds_read_b128 v[220:223], v170 offset:37888
	ds_read_b128 v[224:227], v170 offset:38912
	ds_read_b128 v[228:231], v170 offset:39936
	global_load_lds_dwordx4 v[240:241], off
	s_mov_b32 m0, s50
	v_lshl_add_u64 v[240:241], s[40:41], 0, v[136:137]
	global_load_lds_dwordx4 v[240:241], off
	s_waitcnt vmcnt(8)
	s_waitcnt lgkmcnt(0)
	s_barrier
; #define PG8_STAGE(bufoff, gbase, voff) do { _Pragma("unroll") for (int _i = 0; _i < 2; ++_i) \
;         __builtin_amdgcn_global_load_lds((const unsigned*)((const char*)(gbase) + (voff)[_i]), (PG8_LAS unsigned*)(lds + (bufoff) + ldsw + _i * 8192), 16, 0, 0); } while (0)
; #define PG8_LDA(dst, b, h) do { _Pragma("unroll") for (int m = 0; m < 4; ++m) _Pragma("unroll") for (int k = 0; k < 2; ++k) dst[m][k] = *(const PG8_LAS bf16x8*)(lds + PG8_SA(b, h) + aoff + m * 2048 + k * 1024); } while (0)
; #define PG8_MMA(ai, bj, At, Bt) do { __builtin_amdgcn_s_setprio(1); _Pragma("unroll") for (int m = 0; m < 4; ++m) _Pragma("unroll") for (int n = 0; n < 2; ++n) _Pragma("unroll") for (int k = 0; k < 2; ++k) \
;         acc[ai][bj][m][n] = __builtin_amdgcn_mfma_f32_16x16x32_bf16(Bt[n][k], At[m][k], acc[ai][bj][m][n], 0, 0, 0); __builtin_amdgcn_s_setprio(0); } while (0)
; #define PG8_WAIT_V(n) asm volatile("s_waitcnt vmcnt(" #n ")" ::: "memory")
; #define PG8_WAIT_L(n) asm volatile("s_waitcnt lgkmcnt(" #n ")" ::: "memory")
; #define PG8_BAR __builtin_amdgcn_s_barrier()
; #define PG8_SCHED __builtin_amdgcn_sched_barrier(0)
; template <class Epi, class Sched, bool ALIGN_EPI = false, bool SP2 = false, bool KSEG = false>
; __device__ __forceinline__ void gemm_phase(PG8_LAS unsigned char* lds, const Gemm g, const Sched& S, const Epi& E) {
;     ...
;             PG8_WAIT_V(8); PG8_WAIT_L(0); PG8_BAR; PG8_MMA(0, 0, At, B0); PG8_MMA(0, 1, At, B1); PG8_BAR; PG8_SCHED;
;             PG8_LDA(At, 1, 1); PG8_STAGE(PG8_SB(1, 0), b3, voffB); PG8_STAGE(PG8_SB(1, 1), b3 + hstep, voffB); PG8_STAGE(PG8_SA(1, 0), a3, voffA);
;             PG8_WAIT_V(8); PG8_WAIT_L(0); PG8_BAR; PG8_MMA(1, 0, At, B0); PG8_MMA(1, 1, At, B1); PG8_BAR; PG8_SCHED;
	s_setprio 1
	s_waitcnt lgkmcnt(0)
	v_mfma_f32_16x16x32_bf16 v[126:129], v[148:151], v[200:203], v[126:129]
	v_mfma_f32_16x16x32_bf16 v[122:125], v[176:179], v[200:203], v[122:125]
	v_mfma_f32_16x16x32_bf16 v[110:113], v[148:151], v[208:211], v[110:113]
	v_mfma_f32_16x16x32_bf16 v[106:109], v[176:179], v[208:211], v[106:109]
	v_mfma_f32_16x16x32_bf16 v[94:97], v[148:151], v[216:219], v[94:97]
	v_mfma_f32_16x16x32_bf16 v[90:93], v[176:179], v[216:219], v[90:93]
	v_mfma_f32_16x16x32_bf16 v[78:81], v[148:151], v[224:227], v[78:81]
	v_mfma_f32_16x16x32_bf16 v[74:77], v[176:179], v[224:227], v[74:77]
	v_mfma_f32_16x16x32_bf16 v[126:129], v[172:175], v[204:207], v[126:129]
	v_mfma_f32_16x16x32_bf16 v[122:125], v[180:183], v[204:207], v[122:125]
	v_mfma_f32_16x16x32_bf16 v[110:113], v[172:175], v[212:215], v[110:113]
	v_mfma_f32_16x16x32_bf16 v[106:109], v[180:183], v[212:215], v[106:109]
	v_mfma_f32_16x16x32_bf16 v[94:97], v[172:175], v[220:223], v[94:97]
	v_mfma_f32_16x16x32_bf16 v[90:93], v[180:183], v[220:223], v[90:93]
	v_mfma_f32_16x16x32_bf16 v[78:81], v[172:175], v[228:231], v[78:81]
	v_mfma_f32_16x16x32_bf16 v[74:77], v[180:183], v[228:231], v[74:77]
	s_setprio 0
	s_setprio 1
	v_mfma_f32_16x16x32_bf16 v[118:121], v[184:187], v[200:203], v[118:121]
	v_mfma_f32_16x16x32_bf16 v[114:117], v[192:195], v[200:203], v[114:117]
	v_mfma_f32_16x16x32_bf16 v[102:105], v[184:187], v[208:211], v[102:105]
	v_mfma_f32_16x16x32_bf16 v[98:101], v[192:195], v[208:211], v[98:101]
	v_mfma_f32_16x16x32_bf16 v[86:89], v[184:187], v[216:219], v[86:89]
	v_mfma_f32_16x16x32_bf16 v[82:85], v[192:195], v[216:219], v[82:85]
	v_mfma_f32_16x16x32_bf16 v[70:73], v[184:187], v[224:227], v[70:73]
	v_mfma_f32_16x16x32_bf16 v[66:69], v[192:195], v[224:227], v[66:69]
	v_mfma_f32_16x16x32_bf16 v[118:121], v[188:191], v[204:207], v[118:121]
	v_mfma_f32_16x16x32_bf16 v[114:117], v[196:199], v[204:207], v[114:117]
	v_mfma_f32_16x16x32_bf16 v[102:105], v[188:191], v[212:215], v[102:105]
	v_mfma_f32_16x16x32_bf16 v[98:101], v[196:199], v[212:215], v[98:101]
	v_mfma_f32_16x16x32_bf16 v[86:89], v[188:191], v[220:223], v[86:89]
	v_mfma_f32_16x16x32_bf16 v[82:85], v[196:199], v[220:223], v[82:85]
	v_mfma_f32_16x16x32_bf16 v[70:73], v[188:191], v[228:231], v[70:73]
	v_mfma_f32_16x16x32_bf16 v[66:69], v[196:199], v[228:231], v[66:69]
	s_setprio 0
	s_barrier
	s_add_i32 s33, s33, s43
	v_lshl_add_u64 v[232:233], v[232:233], 0, s[10:11]
	s_mov_b32 m0, s33
	ds_read_b128 v[200:203], v170 offset:49152
	ds_read_b128 v[204:207], v170 offset:50176
	ds_read_b128 v[208:211], v170 offset:51200
	ds_read_b128 v[212:215], v170 offset:52224
	ds_read_b128 v[216:219], v170 offset:53248
	ds_read_b128 v[220:223], v170 offset:54272
	ds_read_b128 v[224:227], v170 offset:55296
	ds_read_b128 v[228:231], v170 offset:56320
	global_load_lds_dwordx4 v[232:233], off
	s_add_i32 m0, s33, 0x2000
	s_add_u32 s38, s38, 0x80080
	v_lshl_add_u64 v[232:233], v[234:235], 0, s[10:11]
	s_addc_u32 s39, s39, 0
	s_add_i32 s33, s63, s43
	global_load_lds_dwordx4 v[232:233], off
	s_mov_b32 m0, s33
	v_lshl_add_u64 v[232:233], s[38:39], 0, v[134:135]
	global_load_lds_dwordx4 v[232:233], off
	s_add_i32 m0, s33, 0x2000
	v_lshl_add_u64 v[232:233], s[38:39], 0, v[138:139]
	global_load_lds_dwordx4 v[232:233], off
	s_waitcnt vmcnt(6)
	s_waitcnt lgkmcnt(0)
	s_barrier
	s_setprio 1
	s_waitcnt lgkmcnt(0)
	v_mfma_f32_16x16x32_bf16 v[62:65], v[148:151], v[200:203], v[62:65]
	v_mfma_f32_16x16x32_bf16 v[58:61], v[176:179], v[200:203], v[58:61]
	v_mfma_f32_16x16x32_bf16 v[46:49], v[148:151], v[208:211], v[46:49]
	v_mfma_f32_16x16x32_bf16 v[42:45], v[176:179], v[208:211], v[42:45]
	v_mfma_f32_16x16x32_bf16 v[30:33], v[148:151], v[216:219], v[30:33]
	v_mfma_f32_16x16x32_bf16 v[26:29], v[176:179], v[216:219], v[26:29]
	v_mfma_f32_16x16x32_bf16 v[14:17], v[148:151], v[224:227], v[14:17]
	v_mfma_f32_16x16x32_bf16 v[10:13], v[176:179], v[224:227], v[10:13]
	v_mfma_f32_16x16x32_bf16 v[62:65], v[172:175], v[204:207], v[62:65]
	v_mfma_f32_16x16x32_bf16 v[58:61], v[180:183], v[204:207], v[58:61]
	v_mfma_f32_16x16x32_bf16 v[46:49], v[172:175], v[212:215], v[46:49]
	v_mfma_f32_16x16x32_bf16 v[42:45], v[180:183], v[212:215], v[42:45]
	v_mfma_f32_16x16x32_bf16 v[30:33], v[172:175], v[220:223], v[30:33]
	v_mfma_f32_16x16x32_bf16 v[26:29], v[180:183], v[220:223], v[26:29]
	v_mfma_f32_16x16x32_bf16 v[14:17], v[172:175], v[228:231], v[14:17]
	v_mfma_f32_16x16x32_bf16 v[10:13], v[180:183], v[228:231], v[10:13]
	s_setprio 0
	s_setprio 1
	v_mfma_f32_16x16x32_bf16 v[54:57], v[184:187], v[200:203], v[54:57]
	v_mfma_f32_16x16x32_bf16 v[50:53], v[192:195], v[200:203], v[50:53]
	v_mfma_f32_16x16x32_bf16 v[38:41], v[184:187], v[208:211], v[38:41]
	v_mfma_f32_16x16x32_bf16 v[34:37], v[192:195], v[208:211], v[34:37]
	v_mfma_f32_16x16x32_bf16 v[22:25], v[184:187], v[216:219], v[22:25]
	v_mfma_f32_16x16x32_bf16 v[18:21], v[192:195], v[216:219], v[18:21]
	v_mfma_f32_16x16x32_bf16 v[6:9], v[184:187], v[224:227], v[6:9]
	v_mfma_f32_16x16x32_bf16 v[2:5], v[192:195], v[224:227], v[2:5]
	v_mfma_f32_16x16x32_bf16 v[54:57], v[188:191], v[204:207], v[54:57]
	v_mfma_f32_16x16x32_bf16 v[50:53], v[196:199], v[204:207], v[50:53]
	v_mfma_f32_16x16x32_bf16 v[38:41], v[188:191], v[212:215], v[38:41]
	v_mfma_f32_16x16x32_bf16 v[34:37], v[196:199], v[212:215], v[34:37]
	v_mfma_f32_16x16x32_bf16 v[22:25], v[188:191], v[220:223], v[22:25]
	v_mfma_f32_16x16x32_bf16 v[18:21], v[196:199], v[220:223], v[18:21]
	v_mfma_f32_16x16x32_bf16 v[6:9], v[188:191], v[228:231], v[6:9]
	v_mfma_f32_16x16x32_bf16 v[2:5], v[196:199], v[228:231], v[2:5]
	s_setprio 0
	s_barrier
	s_add_i32 s62, s62, 2
	s_add_u32 s36, s36, 0x100
	s_addc_u32 s37, s37, 0
	s_add_u32 s60, s60, 0x100
	s_addc_u32 s61, s61, 0
	s_cmp_gt_u32 s62, 29
	s_cbranch_scc0 .LBB0_497
	s_and_b64 vcc, exec, s[12:13]
	s_cbranch_vccz .LBB0_500
	s_barrier

; #define PG8_STAGE(bufoff, gbase, voff) do { _Pragma("unroll") for (int _i = 0; _i < 2; ++_i) \
;         __builtin_amdgcn_global_load_lds((const unsigned*)((const char*)(gbase) + (voff)[_i]), (PG8_LAS unsigned*)(lds + (bufoff) + ldsw + _i * 8192), 16, 0, 0); } while (0)
; #define PG8_LDA(dst, b, h) do { _Pragma("unroll") for (int m = 0; m < 4; ++m) _Pragma("unroll") for (int k = 0; k < 2; ++k) dst[m][k] = *(const PG8_LAS bf16x8*)(lds + PG8_SA(b, h) + aoff + m * 2048 + k * 1024); } while (0)
; #define PG8_LDB(dst, b, h) do { _Pragma("unroll") for (int n = 0; n < 2; ++n) _Pragma("unroll") for (int k = 0; k < 2; ++k) dst[n][k] = *(const PG8_LAS bf16x8*)(lds + PG8_SB(b, h) + boff + n * 2048 + k * 1024); } while (0)
; #define PG8_MMA(ai, bj, At, Bt) do { __builtin_amdgcn_s_setprio(1); _Pragma("unroll") for (int m = 0; m < 4; ++m) _Pragma("unroll") for (int n = 0; n < 2; ++n) _Pragma("unroll") for (int k = 0; k < 2; ++k) \
;         acc[ai][bj][m][n] = __builtin_amdgcn_mfma_f32_16x16x32_bf16(Bt[n][k], At[m][k], acc[ai][bj][m][n], 0, 0, 0); __builtin_amdgcn_s_setprio(0); } while (0)
; #define PG8_WAIT_V(n) asm volatile("s_waitcnt vmcnt(" #n ")" ::: "memory")
; #define PG8_WAIT_L(n) asm volatile("s_waitcnt lgkmcnt(" #n ")" ::: "memory")
; #define PG8_BAR __builtin_amdgcn_s_barrier()
; #define PG8_SCHED __builtin_amdgcn_sched_barrier(0)
; template <class Epi, class Sched, bool ALIGN_EPI = false, bool SP2 = false, bool KSEG = false>
; __device__ __forceinline__ void gemm_phase(PG8_LAS unsigned char* lds, const Gemm g, const Sched& S, const Epi& E) {
;     ...
;             PG8_LDB(B0, 0, 0); PG8_LDB(B1, 0, 1); PG8_SCHED; PG8_LDA(At, 0, 0); PG8_STAGE(PG8_SA(1, 1), a1 + hstep, voffA);
;             PG8_WAIT_V(8); PG8_WAIT_L(0); PG8_BAR; PG8_MMA(0, 0, At, B0); PG8_MMA(0, 1, At, B1); PG8_BAR; PG8_SCHED;
;             PG8_LDA(At, 0, 1); PG8_STAGE(PG8_SB(0, 0), b2, voffB); PG8_STAGE(PG8_SB(0, 1), b2 + hstep, voffB); PG8_STAGE(PG8_SA(0, 0), a2, voffA);
;             PG8_WAIT_V(8); PG8_WAIT_L(0); PG8_BAR; PG8_MMA(1, 0, At, B0); PG8_MMA(1, 1, At, B1); PG8_BAR; PG8_SCHED;
.LBB0_537:
	ds_read_b128 v[154:157], v173
	ds_read_b128 v[176:179], v173 offset:1024
	ds_read_b128 v[180:183], v173 offset:2048
	ds_read_b128 v[184:187], v173 offset:3072
	ds_read_b128 v[188:191], v174
	ds_read_b128 v[192:195], v174 offset:1024
	ds_read_b128 v[196:199], v174 offset:2048
	ds_read_b128 v[200:203], v174 offset:3072
	s_add_u32 s33, s36, 0xffea0080
	s_addc_u32 s38, s37, -1
	s_cmpk_eq_i32 s64, 0x54
	s_cselect_b32 s41, s13, s38
	s_cselect_b32 s40, s12, s33
	s_cselect_b32 s39, s31, s63
	s_cselect_b32 s38, s30, s62
	s_add_u32 s98, s36, 0xffea0000
	s_addc_u32 s99, s37, -1
	s_mov_b32 m0, s54
	v_lshl_add_u64 v[236:237], s[98:99], 0, v[140:141]
	global_load_lds_dwordx4 v[236:237], off
	s_mov_b32 m0, s55
	v_lshl_add_u64 v[236:237], s[98:99], 0, v[142:143]
	global_load_lds_dwordx4 v[236:237], off
	v_lshl_add_u64 v[236:237], s[36:37], 0, v[146:147]
	s_add_i32 m0, s44, 0xc000
	ds_read_b128 v[204:207], v175
	ds_read_b128 v[208:211], v175 offset:1024
	ds_read_b128 v[212:215], v175 offset:2048
	ds_read_b128 v[216:219], v175 offset:3072
	ds_read_b128 v[220:223], v175 offset:4096
	ds_read_b128 v[224:227], v175 offset:5120
	ds_read_b128 v[228:231], v175 offset:6144
	ds_read_b128 v[232:235], v175 offset:7168
	global_load_lds_dwordx4 v[236:237], off
	s_add_i32 m0, s44, 0xe000
	v_lshl_add_u64 v[236:237], s[36:37], 0, v[148:149]
	global_load_lds_dwordx4 v[236:237], off
	s_waitcnt vmcnt(8)
	s_waitcnt lgkmcnt(0)
	s_barrier
	s_setprio 1
	s_waitcnt lgkmcnt(0)
	v_mfma_f32_16x16x32_bf16 v[126:129], v[154:157], v[204:207], v[126:129]
	v_mfma_f32_16x16x32_bf16 v[122:125], v[180:183], v[204:207], v[122:125]
	v_mfma_f32_16x16x32_bf16 v[110:113], v[154:157], v[212:215], v[110:113]
	v_mfma_f32_16x16x32_bf16 v[106:109], v[180:183], v[212:215], v[106:109]
	v_mfma_f32_16x16x32_bf16 v[94:97], v[154:157], v[220:223], v[94:97]
	v_mfma_f32_16x16x32_bf16 v[90:93], v[180:183], v[220:223], v[90:93]
	v_mfma_f32_16x16x32_bf16 v[78:81], v[154:157], v[228:231], v[78:81]
	v_mfma_f32_16x16x32_bf16 v[74:77], v[180:183], v[228:231], v[74:77]
	v_mfma_f32_16x16x32_bf16 v[126:129], v[176:179], v[208:211], v[126:129]
	v_mfma_f32_16x16x32_bf16 v[122:125], v[184:187], v[208:211], v[122:125]
	v_mfma_f32_16x16x32_bf16 v[110:113], v[176:179], v[216:219], v[110:113]
	v_mfma_f32_16x16x32_bf16 v[106:109], v[184:187], v[216:219], v[106:109]
	v_mfma_f32_16x16x32_bf16 v[94:97], v[176:179], v[224:227], v[94:97]
	v_mfma_f32_16x16x32_bf16 v[90:93], v[184:187], v[224:227], v[90:93]
	v_mfma_f32_16x16x32_bf16 v[78:81], v[176:179], v[232:235], v[78:81]
	v_mfma_f32_16x16x32_bf16 v[74:77], v[184:187], v[232:235], v[74:77]
	s_setprio 0
	s_setprio 1
	v_mfma_f32_16x16x32_bf16 v[118:121], v[188:191], v[204:207], v[118:121]
	v_mfma_f32_16x16x32_bf16 v[114:117], v[196:199], v[204:207], v[114:117]
	v_mfma_f32_16x16x32_bf16 v[102:105], v[188:191], v[212:215], v[102:105]
	v_mfma_f32_16x16x32_bf16 v[98:101], v[196:199], v[212:215], v[98:101]
	v_mfma_f32_16x16x32_bf16 v[86:89], v[188:191], v[220:223], v[86:89]
	v_mfma_f32_16x16x32_bf16 v[82:85], v[196:199], v[220:223], v[82:85]
	v_mfma_f32_16x16x32_bf16 v[70:73], v[188:191], v[228:231], v[70:73]
	v_mfma_f32_16x16x32_bf16 v[66:69], v[196:199], v[228:231], v[66:69]
	v_mfma_f32_16x16x32_bf16 v[118:121], v[192:195], v[208:211], v[118:121]
	v_mfma_f32_16x16x32_bf16 v[114:117], v[200:203], v[208:211], v[114:117]
	v_mfma_f32_16x16x32_bf16 v[102:105], v[192:195], v[216:219], v[102:105]
	v_mfma_f32_16x16x32_bf16 v[98:101], v[200:203], v[216:219], v[98:101]
	v_mfma_f32_16x16x32_bf16 v[86:89], v[192:195], v[224:227], v[86:89]
	v_mfma_f32_16x16x32_bf16 v[82:85], v[200:203], v[224:227], v[82:85]
	v_mfma_f32_16x16x32_bf16 v[70:73], v[192:195], v[232:235], v[70:73]
	v_mfma_f32_16x16x32_bf16 v[66:69], v[200:203], v[232:235], v[66:69]
	s_setprio 0
	s_barrier
	s_add_i32 s33, s56, s43
	v_lshl_add_u64 v[236:237], s[38:39], 0, v[130:131]
	s_mov_b32 m0, s33
	ds_read_b128 v[204:207], v175 offset:16384
	ds_read_b128 v[208:211], v175 offset:17408
	ds_read_b128 v[212:215], v175 offset:18432
	ds_read_b128 v[216:219], v175 offset:19456
	ds_read_b128 v[220:223], v175 offset:20480
	ds_read_b128 v[224:227], v175 offset:21504
	ds_read_b128 v[228:231], v175 offset:22528
	ds_read_b128 v[232:235], v175 offset:23552
	global_load_lds_dwordx4 v[236:237], off
	s_add_i32 m0, s33, 0x2000
	s_add_u32 s66, s38, 0x160000
	v_lshl_add_u64 v[238:239], s[38:39], 0, v[144:145]
	s_addc_u32 s67, s39, 0
	s_add_i32 s33, s57, s43
	global_load_lds_dwordx4 v[238:239], off
	s_mov_b32 m0, s33
	v_lshl_add_u64 v[240:241], s[66:67], 0, v[130:131]
	global_load_lds_dwordx4 v[240:241], off
	s_add_i32 m0, s33, 0x2000
	v_lshl_add_u64 v[240:241], s[66:67], 0, v[144:145]
	global_load_lds_dwordx4 v[240:241], off
	s_waitcnt vmcnt(6)
	s_waitcnt lgkmcnt(0)
	s_barrier
; #define PG8_STAGE(bufoff, gbase, voff) do { _Pragma("unroll") for (int _i = 0; _i < 2; ++_i) \
;         __builtin_amdgcn_global_load_lds((const unsigned*)((const char*)(gbase) + (voff)[_i]), (PG8_LAS unsigned*)(lds + (bufoff) + ldsw + _i * 8192), 16, 0, 0); } while (0)
; #define PG8_LDA(dst, b, h) do { _Pragma("unroll") for (int m = 0; m < 4; ++m) _Pragma("unroll") for (int k = 0; k < 2; ++k) dst[m][k] = *(const PG8_LAS bf16x8*)(lds + PG8_SA(b, h) + aoff + m * 2048 + k * 1024); } while (0)
; #define PG8_LDB(dst, b, h) do { _Pragma("unroll") for (int n = 0; n < 2; ++n) _Pragma("unroll") for (int k = 0; k < 2; ++k) dst[n][k] = *(const PG8_LAS bf16x8*)(lds + PG8_SB(b, h) + boff + n * 2048 + k * 1024); } while (0)
; #define PG8_MMA(ai, bj, At, Bt) do { __builtin_amdgcn_s_setprio(1); _Pragma("unroll") for (int m = 0; m < 4; ++m) _Pragma("unroll") for (int n = 0; n < 2; ++n) _Pragma("unroll") for (int k = 0; k < 2; ++k) \
;         acc[ai][bj][m][n] = __builtin_amdgcn_mfma_f32_16x16x32_bf16(Bt[n][k], At[m][k], acc[ai][bj][m][n], 0, 0, 0); __builtin_amdgcn_s_setprio(0); } while (0)
; #define PG8_WAIT_V(n) asm volatile("s_waitcnt vmcnt(" #n ")" ::: "memory")
; #define PG8_WAIT_L(n) asm volatile("s_waitcnt lgkmcnt(" #n ")" ::: "memory")
; #define PG8_BAR __builtin_amdgcn_s_barrier()
; #define PG8_SCHED __builtin_amdgcn_sched_barrier(0)
; template <class Epi, class Sched, bool ALIGN_EPI = false, bool SP2 = false, bool KSEG = false>
; __device__ __forceinline__ void gemm_phase(PG8_LAS unsigned char* lds, const Gemm g, const Sched& S, const Epi& E) {
;     ...
;             PG8_WAIT_V(8); PG8_WAIT_L(0); PG8_BAR; PG8_MMA(1, 0, At, B0); PG8_MMA(1, 1, At, B1); PG8_BAR; PG8_SCHED;
;             PG8_LDB(B0, 1, 0); PG8_LDB(B1, 1, 1); PG8_SCHED; PG8_LDA(At, 1, 0); PG8_STAGE(PG8_SA(0, 1), a2 + hstep, voffA);
;             PG8_WAIT_V(8); PG8_WAIT_L(0); PG8_BAR; PG8_MMA(0, 0, At, B0); PG8_MMA(0, 1, At, B1); PG8_BAR; PG8_SCHED;
	s_setprio 1
	s_waitcnt lgkmcnt(0)
	v_mfma_f32_16x16x32_bf16 v[62:65], v[154:157], v[204:207], v[62:65]
	v_mfma_f32_16x16x32_bf16 v[58:61], v[180:183], v[204:207], v[58:61]
	v_mfma_f32_16x16x32_bf16 v[46:49], v[154:157], v[212:215], v[46:49]
	v_mfma_f32_16x16x32_bf16 v[42:45], v[180:183], v[212:215], v[42:45]
	v_mfma_f32_16x16x32_bf16 v[30:33], v[154:157], v[220:223], v[30:33]
	v_mfma_f32_16x16x32_bf16 v[26:29], v[180:183], v[220:223], v[26:29]
	v_mfma_f32_16x16x32_bf16 v[14:17], v[154:157], v[228:231], v[14:17]
	v_mfma_f32_16x16x32_bf16 v[10:13], v[180:183], v[228:231], v[10:13]
	v_mfma_f32_16x16x32_bf16 v[62:65], v[176:179], v[208:211], v[62:65]
	v_mfma_f32_16x16x32_bf16 v[58:61], v[184:187], v[208:211], v[58:61]
	v_mfma_f32_16x16x32_bf16 v[46:49], v[176:179], v[216:219], v[46:49]
	v_mfma_f32_16x16x32_bf16 v[42:45], v[184:187], v[216:219], v[42:45]
	v_mfma_f32_16x16x32_bf16 v[30:33], v[176:179], v[224:227], v[30:33]
	v_mfma_f32_16x16x32_bf16 v[26:29], v[184:187], v[224:227], v[26:29]
	v_mfma_f32_16x16x32_bf16 v[14:17], v[176:179], v[232:235], v[14:17]
	v_mfma_f32_16x16x32_bf16 v[10:13], v[184:187], v[232:235], v[10:13]
	s_setprio 0
	s_setprio 1
	v_mfma_f32_16x16x32_bf16 v[54:57], v[188:191], v[204:207], v[54:57]
	v_mfma_f32_16x16x32_bf16 v[50:53], v[196:199], v[204:207], v[50:53]
	v_mfma_f32_16x16x32_bf16 v[38:41], v[188:191], v[212:215], v[38:41]
	v_mfma_f32_16x16x32_bf16 v[34:37], v[196:199], v[212:215], v[34:37]
	v_mfma_f32_16x16x32_bf16 v[22:25], v[188:191], v[220:223], v[22:25]
	v_mfma_f32_16x16x32_bf16 v[18:21], v[196:199], v[220:223], v[18:21]
	v_mfma_f32_16x16x32_bf16 v[6:9], v[188:191], v[228:231], v[6:9]
	v_mfma_f32_16x16x32_bf16 v[2:5], v[196:199], v[228:231], v[2:5]
	v_mfma_f32_16x16x32_bf16 v[54:57], v[192:195], v[208:211], v[54:57]
	v_mfma_f32_16x16x32_bf16 v[50:53], v[200:203], v[208:211], v[50:53]
	v_mfma_f32_16x16x32_bf16 v[38:41], v[192:195], v[216:219], v[38:41]
	v_mfma_f32_16x16x32_bf16 v[34:37], v[200:203], v[216:219], v[34:37]
	v_mfma_f32_16x16x32_bf16 v[22:25], v[192:195], v[224:227], v[22:25]
	v_mfma_f32_16x16x32_bf16 v[18:21], v[200:203], v[224:227], v[18:21]
	v_mfma_f32_16x16x32_bf16 v[6:9], v[192:195], v[232:235], v[6:9]
	v_mfma_f32_16x16x32_bf16 v[2:5], v[200:203], v[232:235], v[2:5]
	s_setprio 0
	s_barrier
	s_add_i32 s33, 0, 0x18000
	s_add_i32 s65, 0, 0x1c000
	v_add_u32_e32 v184, s33, v171
	v_add_u32_e32 v200, s65, v171
	ds_read_b128 v[154:157], v184
	ds_read_b128 v[176:179], v184 offset:1024
	ds_read_b128 v[180:183], v184 offset:2048
	ds_read_b128 v[184:187], v184 offset:3072
	ds_read_b128 v[188:191], v200
	ds_read_b128 v[192:195], v200 offset:1024
	ds_read_b128 v[196:199], v200 offset:2048
	ds_read_b128 v[200:203], v200 offset:3072
	s_mov_b32 m0, s44
	v_lshl_add_u64 v[244:245], s[40:41], 0, v[140:141]
	global_load_lds_dwordx4 v[244:245], off
	s_mov_b32 m0, s45
	v_lshl_add_u64 v[244:245], s[40:41], 0, v[142:143]
	global_load_lds_dwordx4 v[244:245], off
	s_add_u32 s40, s40, 0x160000
	s_addc_u32 s41, s41, 0
	s_mov_b32 m0, s51
	v_lshl_add_u64 v[244:245], s[40:41], 0, v[140:141]
	ds_read_b128 v[204:207], v175 offset:32768
	ds_read_b128 v[208:211], v175 offset:33792
	ds_read_b128 v[212:215], v175 offset:34816
	ds_read_b128 v[216:219], v175 offset:35840
	ds_read_b128 v[220:223], v175 offset:36864
	ds_read_b128 v[224:227], v175 offset:37888
	ds_read_b128 v[228:231], v175 offset:38912
	ds_read_b128 v[232:235], v175 offset:39936
	global_load_lds_dwordx4 v[244:245], off
	s_mov_b32 m0, s52
	v_lshl_add_u64 v[244:245], s[40:41], 0, v[142:143]
	global_load_lds_dwordx4 v[244:245], off
	s_waitcnt vmcnt(8)
	s_waitcnt lgkmcnt(0)
	s_barrier
; #define PG8_STAGE(bufoff, gbase, voff) do { _Pragma("unroll") for (int _i = 0; _i < 2; ++_i) \
;         __builtin_amdgcn_global_load_lds((const unsigned*)((const char*)(gbase) + (voff)[_i]), (PG8_LAS unsigned*)(lds + (bufoff) + ldsw + _i * 8192), 16, 0, 0); } while (0)
; #define PG8_LDA(dst, b, h) do { _Pragma("unroll") for (int m = 0; m < 4; ++m) _Pragma("unroll") for (int k = 0; k < 2; ++k) dst[m][k] = *(const PG8_LAS bf16x8*)(lds + PG8_SA(b, h) + aoff + m * 2048 + k * 1024); } while (0)
; #define PG8_MMA(ai, bj, At, Bt) do { __builtin_amdgcn_s_setprio(1); _Pragma("unroll") for (int m = 0; m < 4; ++m) _Pragma("unroll") for (int n = 0; n < 2; ++n) _Pragma("unroll") for (int k = 0; k < 2; ++k) \
;         acc[ai][bj][m][n] = __builtin_amdgcn_mfma_f32_16x16x32_bf16(Bt[n][k], At[m][k], acc[ai][bj][m][n], 0, 0, 0); __builtin_amdgcn_s_setprio(0); } while (0)
; #define PG8_WAIT_V(n) asm volatile("s_waitcnt vmcnt(" #n ")" ::: "memory")
; #define PG8_WAIT_L(n) asm volatile("s_waitcnt lgkmcnt(" #n ")" ::: "memory")
; #define PG8_BAR __builtin_amdgcn_s_barrier()
; #define PG8_SCHED __builtin_amdgcn_sched_barrier(0)
; template <class Epi, class Sched, bool ALIGN_EPI = false, bool SP2 = false, bool KSEG = false>
; __device__ __forceinline__ void gemm_phase(PG8_LAS unsigned char* lds, const Gemm g, const Sched& S, const Epi& E) {
;     ...
;             PG8_WAIT_V(8); PG8_WAIT_L(0); PG8_BAR; PG8_MMA(0, 0, At, B0); PG8_MMA(0, 1, At, B1); PG8_BAR; PG8_SCHED;
;             PG8_LDA(At, 1, 1); PG8_STAGE(PG8_SB(1, 0), b3, voffB); PG8_STAGE(PG8_SB(1, 1), b3 + hstep, voffB); PG8_STAGE(PG8_SA(1, 0), a3, voffA);
;             PG8_WAIT_V(8); PG8_WAIT_L(0); PG8_BAR; PG8_MMA(1, 0, At, B0); PG8_MMA(1, 1, At, B1); PG8_BAR; PG8_SCHED;
	s_setprio 1
	s_waitcnt lgkmcnt(0)
	v_mfma_f32_16x16x32_bf16 v[126:129], v[154:157], v[204:207], v[126:129]
	v_mfma_f32_16x16x32_bf16 v[122:125], v[180:183], v[204:207], v[122:125]
	v_mfma_f32_16x16x32_bf16 v[110:113], v[154:157], v[212:215], v[110:113]
	v_mfma_f32_16x16x32_bf16 v[106:109], v[180:183], v[212:215], v[106:109]
	v_mfma_f32_16x16x32_bf16 v[94:97], v[154:157], v[220:223], v[94:97]
	v_mfma_f32_16x16x32_bf16 v[90:93], v[180:183], v[220:223], v[90:93]
	v_mfma_f32_16x16x32_bf16 v[78:81], v[154:157], v[228:231], v[78:81]
	v_mfma_f32_16x16x32_bf16 v[74:77], v[180:183], v[228:231], v[74:77]
	v_mfma_f32_16x16x32_bf16 v[126:129], v[176:179], v[208:211], v[126:129]
	v_mfma_f32_16x16x32_bf16 v[122:125], v[184:187], v[208:211], v[122:125]
	v_mfma_f32_16x16x32_bf16 v[110:113], v[176:179], v[216:219], v[110:113]
	v_mfma_f32_16x16x32_bf16 v[106:109], v[184:187], v[216:219], v[106:109]
	v_mfma_f32_16x16x32_bf16 v[94:97], v[176:179], v[224:227], v[94:97]
	v_mfma_f32_16x16x32_bf16 v[90:93], v[184:187], v[224:227], v[90:93]
	v_mfma_f32_16x16x32_bf16 v[78:81], v[176:179], v[232:235], v[78:81]
	v_mfma_f32_16x16x32_bf16 v[74:77], v[184:187], v[232:235], v[74:77]
	s_setprio 0
	s_setprio 1
	v_mfma_f32_16x16x32_bf16 v[118:121], v[188:191], v[204:207], v[118:121]
	v_mfma_f32_16x16x32_bf16 v[114:117], v[196:199], v[204:207], v[114:117]
	v_mfma_f32_16x16x32_bf16 v[102:105], v[188:191], v[212:215], v[102:105]
	v_mfma_f32_16x16x32_bf16 v[98:101], v[196:199], v[212:215], v[98:101]
	v_mfma_f32_16x16x32_bf16 v[86:89], v[188:191], v[220:223], v[86:89]
	v_mfma_f32_16x16x32_bf16 v[82:85], v[196:199], v[220:223], v[82:85]
	v_mfma_f32_16x16x32_bf16 v[70:73], v[188:191], v[228:231], v[70:73]
	v_mfma_f32_16x16x32_bf16 v[66:69], v[196:199], v[228:231], v[66:69]
	v_mfma_f32_16x16x32_bf16 v[118:121], v[192:195], v[208:211], v[118:121]
	v_mfma_f32_16x16x32_bf16 v[114:117], v[200:203], v[208:211], v[114:117]
	v_mfma_f32_16x16x32_bf16 v[102:105], v[192:195], v[216:219], v[102:105]
	v_mfma_f32_16x16x32_bf16 v[98:101], v[200:203], v[216:219], v[98:101]
	v_mfma_f32_16x16x32_bf16 v[86:89], v[192:195], v[224:227], v[86:89]
	v_mfma_f32_16x16x32_bf16 v[82:85], v[200:203], v[224:227], v[82:85]
	v_mfma_f32_16x16x32_bf16 v[70:73], v[192:195], v[232:235], v[70:73]
	v_mfma_f32_16x16x32_bf16 v[66:69], v[200:203], v[232:235], v[66:69]
	s_setprio 0
	s_barrier
	s_add_i32 s33, s33, s43
	v_lshl_add_u64 v[236:237], v[236:237], 0, s[26:27]
	s_mov_b32 m0, s33
	ds_read_b128 v[204:207], v175 offset:49152
	ds_read_b128 v[208:211], v175 offset:50176
	ds_read_b128 v[212:215], v175 offset:51200
	ds_read_b128 v[216:219], v175 offset:52224
	ds_read_b128 v[220:223], v175 offset:53248
	ds_read_b128 v[224:227], v175 offset:54272
	ds_read_b128 v[228:231], v175 offset:55296
	ds_read_b128 v[232:235], v175 offset:56320
	global_load_lds_dwordx4 v[236:237], off
	s_add_i32 m0, s33, 0x2000
	s_add_u32 s38, s38, 0x160080
	v_lshl_add_u64 v[236:237], v[238:239], 0, s[26:27]
	s_addc_u32 s39, s39, 0
	s_add_i32 s33, s65, s43
	global_load_lds_dwordx4 v[236:237], off
	s_mov_b32 m0, s33
	v_lshl_add_u64 v[236:237], s[38:39], 0, v[130:131]
	global_load_lds_dwordx4 v[236:237], off
	s_add_i32 m0, s33, 0x2000
	v_lshl_add_u64 v[236:237], s[38:39], 0, v[144:145]
	global_load_lds_dwordx4 v[236:237], off
	s_waitcnt vmcnt(6)
	s_waitcnt lgkmcnt(0)
	s_barrier
	s_setprio 1
	s_waitcnt lgkmcnt(0)
	v_mfma_f32_16x16x32_bf16 v[62:65], v[154:157], v[204:207], v[62:65]
	v_mfma_f32_16x16x32_bf16 v[58:61], v[180:183], v[204:207], v[58:61]
	v_mfma_f32_16x16x32_bf16 v[46:49], v[154:157], v[212:215], v[46:49]
	v_mfma_f32_16x16x32_bf16 v[42:45], v[180:183], v[212:215], v[42:45]
	v_mfma_f32_16x16x32_bf16 v[30:33], v[154:157], v[220:223], v[30:33]
	v_mfma_f32_16x16x32_bf16 v[26:29], v[180:183], v[220:223], v[26:29]
	v_mfma_f32_16x16x32_bf16 v[14:17], v[154:157], v[228:231], v[14:17]
	v_mfma_f32_16x16x32_bf16 v[10:13], v[180:183], v[228:231], v[10:13]
	v_mfma_f32_16x16x32_bf16 v[62:65], v[176:179], v[208:211], v[62:65]
	v_mfma_f32_16x16x32_bf16 v[58:61], v[184:187], v[208:211], v[58:61]
	v_mfma_f32_16x16x32_bf16 v[46:49], v[176:179], v[216:219], v[46:49]
	v_mfma_f32_16x16x32_bf16 v[42:45], v[184:187], v[216:219], v[42:45]
	v_mfma_f32_16x16x32_bf16 v[30:33], v[176:179], v[224:227], v[30:33]
	v_mfma_f32_16x16x32_bf16 v[26:29], v[184:187], v[224:227], v[26:29]
	v_mfma_f32_16x16x32_bf16 v[14:17], v[176:179], v[232:235], v[14:17]
	v_mfma_f32_16x16x32_bf16 v[10:13], v[184:187], v[232:235], v[10:13]
	s_setprio 0
	s_setprio 1
	v_mfma_f32_16x16x32_bf16 v[54:57], v[188:191], v[204:207], v[54:57]
	v_mfma_f32_16x16x32_bf16 v[50:53], v[196:199], v[204:207], v[50:53]
	v_mfma_f32_16x16x32_bf16 v[38:41], v[188:191], v[212:215], v[38:41]
	v_mfma_f32_16x16x32_bf16 v[34:37], v[196:199], v[212:215], v[34:37]
	v_mfma_f32_16x16x32_bf16 v[22:25], v[188:191], v[220:223], v[22:25]
	v_mfma_f32_16x16x32_bf16 v[18:21], v[196:199], v[220:223], v[18:21]
	v_mfma_f32_16x16x32_bf16 v[6:9], v[188:191], v[228:231], v[6:9]
	v_mfma_f32_16x16x32_bf16 v[2:5], v[196:199], v[228:231], v[2:5]
	v_mfma_f32_16x16x32_bf16 v[54:57], v[192:195], v[208:211], v[54:57]
	v_mfma_f32_16x16x32_bf16 v[50:53], v[200:203], v[208:211], v[50:53]
	v_mfma_f32_16x16x32_bf16 v[38:41], v[192:195], v[216:219], v[38:41]
	v_mfma_f32_16x16x32_bf16 v[34:37], v[200:203], v[216:219], v[34:37]
	v_mfma_f32_16x16x32_bf16 v[22:25], v[192:195], v[224:227], v[22:25]
	v_mfma_f32_16x16x32_bf16 v[18:21], v[200:203], v[224:227], v[18:21]
	v_mfma_f32_16x16x32_bf16 v[6:9], v[192:195], v[232:235], v[6:9]
	v_mfma_f32_16x16x32_bf16 v[2:5], v[200:203], v[232:235], v[2:5]
	s_setprio 0
	s_barrier
	s_add_i32 s64, s64, 2
	s_add_u32 s36, s36, 0x100
	s_addc_u32 s37, s37, 0
	s_add_u32 s62, s62, 0x100
	s_addc_u32 s63, s63, 0
	s_cmpk_gt_u32 s64, 0x55
	s_cbranch_scc0 .LBB0_537
	s_and_b64 vcc, exec, s[28:29]
	s_cbranch_vccz .LBB0_540
	s_barrier

; #define PG8_STAGE(bufoff, gbase, voff) do { _Pragma("unroll") for (int _i = 0; _i < 2; ++_i) \
;         __builtin_amdgcn_global_load_lds((const unsigned*)((const char*)(gbase) + (voff)[_i]), (PG8_LAS unsigned*)(lds + (bufoff) + ldsw + _i * 8192), 16, 0, 0); } while (0)
; #define PG8_LDA(dst, b, h) do { _Pragma("unroll") for (int m = 0; m < 4; ++m) _Pragma("unroll") for (int k = 0; k < 2; ++k) dst[m][k] = *(const PG8_LAS bf16x8*)(lds + PG8_SA(b, h) + aoff + m * 2048 + k * 1024); } while (0)
; #define PG8_LDB(dst, b, h) do { _Pragma("unroll") for (int n = 0; n < 2; ++n) _Pragma("unroll") for (int k = 0; k < 2; ++k) dst[n][k] = *(const PG8_LAS bf16x8*)(lds + PG8_SB(b, h) + boff + n * 2048 + k * 1024); } while (0)
; #define PG8_MMA(ai, bj, At, Bt) do { __builtin_amdgcn_s_setprio(1); _Pragma("unroll") for (int m = 0; m < 4; ++m) _Pragma("unroll") for (int n = 0; n < 2; ++n) _Pragma("unroll") for (int k = 0; k < 2; ++k) \
;         acc[ai][bj][m][n] = __builtin_amdgcn_mfma_f32_16x16x32_bf16(Bt[n][k], At[m][k], acc[ai][bj][m][n], 0, 0, 0); __builtin_amdgcn_s_setprio(0); } while (0)
; #define PG8_WAIT_V(n) asm volatile("s_waitcnt vmcnt(" #n ")" ::: "memory")
; #define PG8_WAIT_L(n) asm volatile("s_waitcnt lgkmcnt(" #n ")" ::: "memory")
; #define PG8_BAR __builtin_amdgcn_s_barrier()
; #define PG8_SCHED __builtin_amdgcn_sched_barrier(0)
; template <class Epi, class Sched, bool ALIGN_EPI = false, bool SP2 = false, bool KSEG = false>
; __device__ __forceinline__ void gemm_phase(PG8_LAS unsigned char* lds, const Gemm g, const Sched& S, const Epi& E) {
;     ...
;             PG8_LDB(B0, 0, 0); PG8_LDB(B1, 0, 1); PG8_SCHED; PG8_LDA(At, 0, 0); PG8_STAGE(PG8_SA(1, 1), a1 + hstep, voffA);
;             PG8_WAIT_V(8); PG8_WAIT_L(0); PG8_BAR; PG8_MMA(0, 0, At, B0); PG8_MMA(0, 1, At, B1); PG8_BAR; PG8_SCHED;
;             PG8_LDA(At, 0, 1); PG8_STAGE(PG8_SB(0, 0), b2, voffB); PG8_STAGE(PG8_SB(0, 1), b2 + hstep, voffB); PG8_STAGE(PG8_SA(0, 0), a2, voffA);
;             PG8_WAIT_V(8); PG8_WAIT_L(0); PG8_BAR; PG8_MMA(1, 0, At, B0); PG8_MMA(1, 1, At, B1); PG8_BAR; PG8_SCHED;
.LBB0_581:
	ds_read_b128 v[154:157], v160
	ds_read_b128 v[172:175], v160 offset:1024
	ds_read_b128 v[176:179], v160 offset:2048
	ds_read_b128 v[180:183], v160 offset:3072
	ds_read_b128 v[184:187], v161
	ds_read_b128 v[188:191], v161 offset:1024
	ds_read_b128 v[192:195], v161 offset:2048
	ds_read_b128 v[196:199], v161 offset:3072
	s_add_u32 s33, s40, 0xfff80080
	s_addc_u32 s42, s41, -1
	s_cmp_eq_u32 s79, 28
	s_cselect_b32 s45, s29, s42
	s_cselect_b32 s44, s65, s33
	s_cselect_b32 s43, s27, s78
	s_cselect_b32 s42, s66, s67
	s_add_u32 s98, s40, 0xfff80000
	s_addc_u32 s99, s41, -1
	s_mov_b32 m0, s60
	v_lshl_add_u64 v[232:233], s[98:99], 0, v[132:133]
	global_load_lds_dwordx4 v[232:233], off
	s_mov_b32 m0, s61
	v_lshl_add_u64 v[232:233], s[98:99], 0, v[136:137]
	global_load_lds_dwordx4 v[232:233], off
	v_lshl_add_u64 v[232:233], s[40:41], 0, v[146:147]
	s_add_i32 m0, s55, 0xc000
	ds_read_b128 v[200:203], v164
	ds_read_b128 v[204:207], v164 offset:1024
	ds_read_b128 v[208:211], v164 offset:2048
	ds_read_b128 v[212:215], v164 offset:3072
	ds_read_b128 v[216:219], v164 offset:4096
	ds_read_b128 v[220:223], v164 offset:5120
	ds_read_b128 v[224:227], v164 offset:6144
	ds_read_b128 v[228:231], v164 offset:7168
	global_load_lds_dwordx4 v[232:233], off
	s_add_i32 m0, s55, 0xe000
	v_lshl_add_u64 v[232:233], s[40:41], 0, v[148:149]
	global_load_lds_dwordx4 v[232:233], off
	s_waitcnt vmcnt(8)
	s_waitcnt lgkmcnt(0)
	s_barrier
	s_setprio 1
	s_waitcnt lgkmcnt(0)
	v_mfma_f32_16x16x32_bf16 v[126:129], v[154:157], v[200:203], v[126:129]
	v_mfma_f32_16x16x32_bf16 v[122:125], v[176:179], v[200:203], v[122:125]
	v_mfma_f32_16x16x32_bf16 v[110:113], v[154:157], v[208:211], v[110:113]
	v_mfma_f32_16x16x32_bf16 v[106:109], v[176:179], v[208:211], v[106:109]
	v_mfma_f32_16x16x32_bf16 v[94:97], v[154:157], v[216:219], v[94:97]
	v_mfma_f32_16x16x32_bf16 v[90:93], v[176:179], v[216:219], v[90:93]
	v_mfma_f32_16x16x32_bf16 v[78:81], v[154:157], v[224:227], v[78:81]
	v_mfma_f32_16x16x32_bf16 v[74:77], v[176:179], v[224:227], v[74:77]
	v_mfma_f32_16x16x32_bf16 v[126:129], v[172:175], v[204:207], v[126:129]
	v_mfma_f32_16x16x32_bf16 v[122:125], v[180:183], v[204:207], v[122:125]
	v_mfma_f32_16x16x32_bf16 v[110:113], v[172:175], v[212:215], v[110:113]
	v_mfma_f32_16x16x32_bf16 v[106:109], v[180:183], v[212:215], v[106:109]
	v_mfma_f32_16x16x32_bf16 v[94:97], v[172:175], v[220:223], v[94:97]
	v_mfma_f32_16x16x32_bf16 v[90:93], v[180:183], v[220:223], v[90:93]
	v_mfma_f32_16x16x32_bf16 v[78:81], v[172:175], v[228:231], v[78:81]
	v_mfma_f32_16x16x32_bf16 v[74:77], v[180:183], v[228:231], v[74:77]
	s_setprio 0
	s_setprio 1
	v_mfma_f32_16x16x32_bf16 v[118:121], v[184:187], v[200:203], v[118:121]
	v_mfma_f32_16x16x32_bf16 v[114:117], v[192:195], v[200:203], v[114:117]
	v_mfma_f32_16x16x32_bf16 v[102:105], v[184:187], v[208:211], v[102:105]
	v_mfma_f32_16x16x32_bf16 v[98:101], v[192:195], v[208:211], v[98:101]
	v_mfma_f32_16x16x32_bf16 v[86:89], v[184:187], v[216:219], v[86:89]
	v_mfma_f32_16x16x32_bf16 v[82:85], v[192:195], v[216:219], v[82:85]
	v_mfma_f32_16x16x32_bf16 v[70:73], v[184:187], v[224:227], v[70:73]
	v_mfma_f32_16x16x32_bf16 v[66:69], v[192:195], v[224:227], v[66:69]
	v_mfma_f32_16x16x32_bf16 v[118:121], v[188:191], v[204:207], v[118:121]
	v_mfma_f32_16x16x32_bf16 v[114:117], v[196:199], v[204:207], v[114:117]
	v_mfma_f32_16x16x32_bf16 v[102:105], v[188:191], v[212:215], v[102:105]
	v_mfma_f32_16x16x32_bf16 v[98:101], v[196:199], v[212:215], v[98:101]
	v_mfma_f32_16x16x32_bf16 v[86:89], v[188:191], v[220:223], v[86:89]
	v_mfma_f32_16x16x32_bf16 v[82:85], v[196:199], v[220:223], v[82:85]
	v_mfma_f32_16x16x32_bf16 v[70:73], v[188:191], v[228:231], v[70:73]
	v_mfma_f32_16x16x32_bf16 v[66:69], v[196:199], v[228:231], v[66:69]
	s_setprio 0
	s_barrier
	s_add_i32 s33, s62, s53
	v_lshl_add_u64 v[232:233], s[42:43], 0, v[134:135]
	s_mov_b32 m0, s33
	ds_read_b128 v[200:203], v164 offset:16384
	ds_read_b128 v[204:207], v164 offset:17408
	ds_read_b128 v[208:211], v164 offset:18432
	ds_read_b128 v[212:215], v164 offset:19456
	ds_read_b128 v[216:219], v164 offset:20480
	ds_read_b128 v[220:223], v164 offset:21504
	ds_read_b128 v[224:227], v164 offset:22528
	ds_read_b128 v[228:231], v164 offset:23552
	global_load_lds_dwordx4 v[232:233], off
	s_add_i32 m0, s33, 0x2000
	s_add_u32 s80, s42, 0x80000
	v_lshl_add_u64 v[234:235], s[42:43], 0, v[138:139]
	s_addc_u32 s81, s43, 0
	s_add_i32 s33, s63, s53
	global_load_lds_dwordx4 v[234:235], off
	s_mov_b32 m0, s33
	v_lshl_add_u64 v[236:237], s[80:81], 0, v[134:135]
	global_load_lds_dwordx4 v[236:237], off
	s_add_i32 m0, s33, 0x2000
	v_lshl_add_u64 v[236:237], s[80:81], 0, v[138:139]
	global_load_lds_dwordx4 v[236:237], off
	s_waitcnt vmcnt(6)
	s_waitcnt lgkmcnt(0)
	s_barrier
; #define PG8_STAGE(bufoff, gbase, voff) do { _Pragma("unroll") for (int _i = 0; _i < 2; ++_i) \
;         __builtin_amdgcn_global_load_lds((const unsigned*)((const char*)(gbase) + (voff)[_i]), (PG8_LAS unsigned*)(lds + (bufoff) + ldsw + _i * 8192), 16, 0, 0); } while (0)
; #define PG8_LDA(dst, b, h) do { _Pragma("unroll") for (int m = 0; m < 4; ++m) _Pragma("unroll") for (int k = 0; k < 2; ++k) dst[m][k] = *(const PG8_LAS bf16x8*)(lds + PG8_SA(b, h) + aoff + m * 2048 + k * 1024); } while (0)
; #define PG8_LDB(dst, b, h) do { _Pragma("unroll") for (int n = 0; n < 2; ++n) _Pragma("unroll") for (int k = 0; k < 2; ++k) dst[n][k] = *(const PG8_LAS bf16x8*)(lds + PG8_SB(b, h) + boff + n * 2048 + k * 1024); } while (0)
; #define PG8_MMA(ai, bj, At, Bt) do { __builtin_amdgcn_s_setprio(1); _Pragma("unroll") for (int m = 0; m < 4; ++m) _Pragma("unroll") for (int n = 0; n < 2; ++n) _Pragma("unroll") for (int k = 0; k < 2; ++k) \
;         acc[ai][bj][m][n] = __builtin_amdgcn_mfma_f32_16x16x32_bf16(Bt[n][k], At[m][k], acc[ai][bj][m][n], 0, 0, 0); __builtin_amdgcn_s_setprio(0); } while (0)
; #define PG8_WAIT_V(n) asm volatile("s_waitcnt vmcnt(" #n ")" ::: "memory")
; #define PG8_WAIT_L(n) asm volatile("s_waitcnt lgkmcnt(" #n ")" ::: "memory")
; #define PG8_BAR __builtin_amdgcn_s_barrier()
; #define PG8_SCHED __builtin_amdgcn_sched_barrier(0)
; template <class Epi, class Sched, bool ALIGN_EPI = false, bool SP2 = false, bool KSEG = false>
; __device__ __forceinline__ void gemm_phase(PG8_LAS unsigned char* lds, const Gemm g, const Sched& S, const Epi& E) {
;     ...
;             PG8_WAIT_V(8); PG8_WAIT_L(0); PG8_BAR; PG8_MMA(1, 0, At, B0); PG8_MMA(1, 1, At, B1); PG8_BAR; PG8_SCHED;
;             PG8_LDB(B0, 1, 0); PG8_LDB(B1, 1, 1); PG8_SCHED; PG8_LDA(At, 1, 0); PG8_STAGE(PG8_SA(0, 1), a2 + hstep, voffA);
;             PG8_WAIT_V(8); PG8_WAIT_L(0); PG8_BAR; PG8_MMA(0, 0, At, B0); PG8_MMA(0, 1, At, B1); PG8_BAR; PG8_SCHED;
	s_setprio 1
	s_waitcnt lgkmcnt(0)
	v_mfma_f32_16x16x32_bf16 v[62:65], v[154:157], v[200:203], v[62:65]
	v_mfma_f32_16x16x32_bf16 v[58:61], v[176:179], v[200:203], v[58:61]
	v_mfma_f32_16x16x32_bf16 v[46:49], v[154:157], v[208:211], v[46:49]
	v_mfma_f32_16x16x32_bf16 v[42:45], v[176:179], v[208:211], v[42:45]
	v_mfma_f32_16x16x32_bf16 v[30:33], v[154:157], v[216:219], v[30:33]
	v_mfma_f32_16x16x32_bf16 v[26:29], v[176:179], v[216:219], v[26:29]
	v_mfma_f32_16x16x32_bf16 v[14:17], v[154:157], v[224:227], v[14:17]
	v_mfma_f32_16x16x32_bf16 v[10:13], v[176:179], v[224:227], v[10:13]
	v_mfma_f32_16x16x32_bf16 v[62:65], v[172:175], v[204:207], v[62:65]
	v_mfma_f32_16x16x32_bf16 v[58:61], v[180:183], v[204:207], v[58:61]
	v_mfma_f32_16x16x32_bf16 v[46:49], v[172:175], v[212:215], v[46:49]
	v_mfma_f32_16x16x32_bf16 v[42:45], v[180:183], v[212:215], v[42:45]
	v_mfma_f32_16x16x32_bf16 v[30:33], v[172:175], v[220:223], v[30:33]
	v_mfma_f32_16x16x32_bf16 v[26:29], v[180:183], v[220:223], v[26:29]
	v_mfma_f32_16x16x32_bf16 v[14:17], v[172:175], v[228:231], v[14:17]
	v_mfma_f32_16x16x32_bf16 v[10:13], v[180:183], v[228:231], v[10:13]
	s_setprio 0
	s_setprio 1
	v_mfma_f32_16x16x32_bf16 v[54:57], v[184:187], v[200:203], v[54:57]
	v_mfma_f32_16x16x32_bf16 v[50:53], v[192:195], v[200:203], v[50:53]
	v_mfma_f32_16x16x32_bf16 v[38:41], v[184:187], v[208:211], v[38:41]
	v_mfma_f32_16x16x32_bf16 v[34:37], v[192:195], v[208:211], v[34:37]
	v_mfma_f32_16x16x32_bf16 v[22:25], v[184:187], v[216:219], v[22:25]
	v_mfma_f32_16x16x32_bf16 v[18:21], v[192:195], v[216:219], v[18:21]
	v_mfma_f32_16x16x32_bf16 v[6:9], v[184:187], v[224:227], v[6:9]
	v_mfma_f32_16x16x32_bf16 v[2:5], v[192:195], v[224:227], v[2:5]
	v_mfma_f32_16x16x32_bf16 v[54:57], v[188:191], v[204:207], v[54:57]
	v_mfma_f32_16x16x32_bf16 v[50:53], v[196:199], v[204:207], v[50:53]
	v_mfma_f32_16x16x32_bf16 v[38:41], v[188:191], v[212:215], v[38:41]
	v_mfma_f32_16x16x32_bf16 v[34:37], v[196:199], v[212:215], v[34:37]
	v_mfma_f32_16x16x32_bf16 v[22:25], v[188:191], v[220:223], v[22:25]
	v_mfma_f32_16x16x32_bf16 v[18:21], v[196:199], v[220:223], v[18:21]
	v_mfma_f32_16x16x32_bf16 v[6:9], v[188:191], v[228:231], v[6:9]
	v_mfma_f32_16x16x32_bf16 v[2:5], v[196:199], v[228:231], v[2:5]
	s_setprio 0
	s_barrier
	s_add_i32 s33, 0, 0x18000
	s_add_i32 s80, 0, 0x1c000
	v_add_u32_e32 v180, s33, v163
	v_add_u32_e32 v196, s80, v163
	ds_read_b128 v[154:157], v180
	ds_read_b128 v[172:175], v180 offset:1024
	ds_read_b128 v[176:179], v180 offset:2048
	ds_read_b128 v[180:183], v180 offset:3072
	ds_read_b128 v[184:187], v196
	ds_read_b128 v[188:191], v196 offset:1024
	ds_read_b128 v[192:195], v196 offset:2048
	ds_read_b128 v[196:199], v196 offset:3072
	s_mov_b32 m0, s55
	v_lshl_add_u64 v[240:241], s[44:45], 0, v[132:133]
	global_load_lds_dwordx4 v[240:241], off
	s_mov_b32 m0, s56
	v_lshl_add_u64 v[240:241], s[44:45], 0, v[136:137]
	global_load_lds_dwordx4 v[240:241], off
	s_add_u32 s44, s44, 0x80000
	s_addc_u32 s45, s45, 0
	s_mov_b32 m0, s57
	v_lshl_add_u64 v[240:241], s[44:45], 0, v[132:133]
	ds_read_b128 v[200:203], v164 offset:32768
	ds_read_b128 v[204:207], v164 offset:33792
	ds_read_b128 v[208:211], v164 offset:34816
	ds_read_b128 v[212:215], v164 offset:35840
	ds_read_b128 v[216:219], v164 offset:36864
	ds_read_b128 v[220:223], v164 offset:37888
	ds_read_b128 v[224:227], v164 offset:38912
	ds_read_b128 v[228:231], v164 offset:39936
	global_load_lds_dwordx4 v[240:241], off
	s_mov_b32 m0, s58
	v_lshl_add_u64 v[240:241], s[44:45], 0, v[136:137]
	global_load_lds_dwordx4 v[240:241], off
	s_waitcnt vmcnt(8)
	s_waitcnt lgkmcnt(0)
	s_barrier
; #define PG8_STAGE(bufoff, gbase, voff) do { _Pragma("unroll") for (int _i = 0; _i < 2; ++_i) \
;         __builtin_amdgcn_global_load_lds((const unsigned*)((const char*)(gbase) + (voff)[_i]), (PG8_LAS unsigned*)(lds + (bufoff) + ldsw + _i * 8192), 16, 0, 0); } while (0)
; #define PG8_LDA(dst, b, h) do { _Pragma("unroll") for (int m = 0; m < 4; ++m) _Pragma("unroll") for (int k = 0; k < 2; ++k) dst[m][k] = *(const PG8_LAS bf16x8*)(lds + PG8_SA(b, h) + aoff + m * 2048 + k * 1024); } while (0)
; #define PG8_MMA(ai, bj, At, Bt) do { __builtin_amdgcn_s_setprio(1); _Pragma("unroll") for (int m = 0; m < 4; ++m) _Pragma("unroll") for (int n = 0; n < 2; ++n) _Pragma("unroll") for (int k = 0; k < 2; ++k) \
;         acc[ai][bj][m][n] = __builtin_amdgcn_mfma_f32_16x16x32_bf16(Bt[n][k], At[m][k], acc[ai][bj][m][n], 0, 0, 0); __builtin_amdgcn_s_setprio(0); } while (0)
; #define PG8_WAIT_V(n) asm volatile("s_waitcnt vmcnt(" #n ")" ::: "memory")
; #define PG8_WAIT_L(n) asm volatile("s_waitcnt lgkmcnt(" #n ")" ::: "memory")
; #define PG8_BAR __builtin_amdgcn_s_barrier()
; #define PG8_SCHED __builtin_amdgcn_sched_barrier(0)
; template <class Epi, class Sched, bool ALIGN_EPI = false, bool SP2 = false, bool KSEG = false>
; __device__ __forceinline__ void gemm_phase(PG8_LAS unsigned char* lds, const Gemm g, const Sched& S, const Epi& E) {
;     ...
;             PG8_WAIT_V(8); PG8_WAIT_L(0); PG8_BAR; PG8_MMA(0, 0, At, B0); PG8_MMA(0, 1, At, B1); PG8_BAR; PG8_SCHED;
;             PG8_LDA(At, 1, 1); PG8_STAGE(PG8_SB(1, 0), b3, voffB); PG8_STAGE(PG8_SB(1, 1), b3 + hstep, voffB); PG8_STAGE(PG8_SA(1, 0), a3, voffA);
;             PG8_WAIT_V(8); PG8_WAIT_L(0); PG8_BAR; PG8_MMA(1, 0, At, B0); PG8_MMA(1, 1, At, B1); PG8_BAR; PG8_SCHED;
	s_setprio 1
	s_waitcnt lgkmcnt(0)
	v_mfma_f32_16x16x32_bf16 v[126:129], v[154:157], v[200:203], v[126:129]
	v_mfma_f32_16x16x32_bf16 v[122:125], v[176:179], v[200:203], v[122:125]
	v_mfma_f32_16x16x32_bf16 v[110:113], v[154:157], v[208:211], v[110:113]
	v_mfma_f32_16x16x32_bf16 v[106:109], v[176:179], v[208:211], v[106:109]
	v_mfma_f32_16x16x32_bf16 v[94:97], v[154:157], v[216:219], v[94:97]
	v_mfma_f32_16x16x32_bf16 v[90:93], v[176:179], v[216:219], v[90:93]
	v_mfma_f32_16x16x32_bf16 v[78:81], v[154:157], v[224:227], v[78:81]
	v_mfma_f32_16x16x32_bf16 v[74:77], v[176:179], v[224:227], v[74:77]
	v_mfma_f32_16x16x32_bf16 v[126:129], v[172:175], v[204:207], v[126:129]
	v_mfma_f32_16x16x32_bf16 v[122:125], v[180:183], v[204:207], v[122:125]
	v_mfma_f32_16x16x32_bf16 v[110:113], v[172:175], v[212:215], v[110:113]
	v_mfma_f32_16x16x32_bf16 v[106:109], v[180:183], v[212:215], v[106:109]
	v_mfma_f32_16x16x32_bf16 v[94:97], v[172:175], v[220:223], v[94:97]
	v_mfma_f32_16x16x32_bf16 v[90:93], v[180:183], v[220:223], v[90:93]
	v_mfma_f32_16x16x32_bf16 v[78:81], v[172:175], v[228:231], v[78:81]
	v_mfma_f32_16x16x32_bf16 v[74:77], v[180:183], v[228:231], v[74:77]
	s_setprio 0
	s_setprio 1
	v_mfma_f32_16x16x32_bf16 v[118:121], v[184:187], v[200:203], v[118:121]
	v_mfma_f32_16x16x32_bf16 v[114:117], v[192:195], v[200:203], v[114:117]
	v_mfma_f32_16x16x32_bf16 v[102:105], v[184:187], v[208:211], v[102:105]
	v_mfma_f32_16x16x32_bf16 v[98:101], v[192:195], v[208:211], v[98:101]
	v_mfma_f32_16x16x32_bf16 v[86:89], v[184:187], v[216:219], v[86:89]
	v_mfma_f32_16x16x32_bf16 v[82:85], v[192:195], v[216:219], v[82:85]
	v_mfma_f32_16x16x32_bf16 v[70:73], v[184:187], v[224:227], v[70:73]
	v_mfma_f32_16x16x32_bf16 v[66:69], v[192:195], v[224:227], v[66:69]
	v_mfma_f32_16x16x32_bf16 v[118:121], v[188:191], v[204:207], v[118:121]
	v_mfma_f32_16x16x32_bf16 v[114:117], v[196:199], v[204:207], v[114:117]
	v_mfma_f32_16x16x32_bf16 v[102:105], v[188:191], v[212:215], v[102:105]
	v_mfma_f32_16x16x32_bf16 v[98:101], v[196:199], v[212:215], v[98:101]
	v_mfma_f32_16x16x32_bf16 v[86:89], v[188:191], v[220:223], v[86:89]
	v_mfma_f32_16x16x32_bf16 v[82:85], v[196:199], v[220:223], v[82:85]
	v_mfma_f32_16x16x32_bf16 v[70:73], v[188:191], v[228:231], v[70:73]
	v_mfma_f32_16x16x32_bf16 v[66:69], v[196:199], v[228:231], v[66:69]
	s_setprio 0
	s_barrier
	s_add_i32 s33, s33, s53
	v_lshl_add_u64 v[232:233], v[232:233], 0, s[12:13]
	s_mov_b32 m0, s33
	ds_read_b128 v[200:203], v164 offset:49152
	ds_read_b128 v[204:207], v164 offset:50176
	ds_read_b128 v[208:211], v164 offset:51200
	ds_read_b128 v[212:215], v164 offset:52224
	ds_read_b128 v[216:219], v164 offset:53248
	ds_read_b128 v[220:223], v164 offset:54272
	ds_read_b128 v[224:227], v164 offset:55296
	ds_read_b128 v[228:231], v164 offset:56320
	global_load_lds_dwordx4 v[232:233], off
	s_add_i32 m0, s33, 0x2000
	s_add_u32 s42, s42, 0x80080
	v_lshl_add_u64 v[232:233], v[234:235], 0, s[12:13]
	s_addc_u32 s43, s43, 0
	s_add_i32 s33, s80, s53
	global_load_lds_dwordx4 v[232:233], off
	s_mov_b32 m0, s33
	v_lshl_add_u64 v[232:233], s[42:43], 0, v[134:135]
	global_load_lds_dwordx4 v[232:233], off
	s_add_i32 m0, s33, 0x2000
	v_lshl_add_u64 v[232:233], s[42:43], 0, v[138:139]
	global_load_lds_dwordx4 v[232:233], off
	s_waitcnt vmcnt(6)
	s_waitcnt lgkmcnt(0)
	s_barrier
	s_setprio 1
	s_waitcnt lgkmcnt(0)
	v_mfma_f32_16x16x32_bf16 v[62:65], v[154:157], v[200:203], v[62:65]
	v_mfma_f32_16x16x32_bf16 v[58:61], v[176:179], v[200:203], v[58:61]
	v_mfma_f32_16x16x32_bf16 v[46:49], v[154:157], v[208:211], v[46:49]
	v_mfma_f32_16x16x32_bf16 v[42:45], v[176:179], v[208:211], v[42:45]
	v_mfma_f32_16x16x32_bf16 v[30:33], v[154:157], v[216:219], v[30:33]
	v_mfma_f32_16x16x32_bf16 v[26:29], v[176:179], v[216:219], v[26:29]
	v_mfma_f32_16x16x32_bf16 v[14:17], v[154:157], v[224:227], v[14:17]
	v_mfma_f32_16x16x32_bf16 v[10:13], v[176:179], v[224:227], v[10:13]
	v_mfma_f32_16x16x32_bf16 v[62:65], v[172:175], v[204:207], v[62:65]
	v_mfma_f32_16x16x32_bf16 v[58:61], v[180:183], v[204:207], v[58:61]
	v_mfma_f32_16x16x32_bf16 v[46:49], v[172:175], v[212:215], v[46:49]
	v_mfma_f32_16x16x32_bf16 v[42:45], v[180:183], v[212:215], v[42:45]
	v_mfma_f32_16x16x32_bf16 v[30:33], v[172:175], v[220:223], v[30:33]
	v_mfma_f32_16x16x32_bf16 v[26:29], v[180:183], v[220:223], v[26:29]
	v_mfma_f32_16x16x32_bf16 v[14:17], v[172:175], v[228:231], v[14:17]
	v_mfma_f32_16x16x32_bf16 v[10:13], v[180:183], v[228:231], v[10:13]
	s_setprio 0
	s_setprio 1
	v_mfma_f32_16x16x32_bf16 v[54:57], v[184:187], v[200:203], v[54:57]
	v_mfma_f32_16x16x32_bf16 v[50:53], v[192:195], v[200:203], v[50:53]
	v_mfma_f32_16x16x32_bf16 v[38:41], v[184:187], v[208:211], v[38:41]
	v_mfma_f32_16x16x32_bf16 v[34:37], v[192:195], v[208:211], v[34:37]
	v_mfma_f32_16x16x32_bf16 v[22:25], v[184:187], v[216:219], v[22:25]
	v_mfma_f32_16x16x32_bf16 v[18:21], v[192:195], v[216:219], v[18:21]
	v_mfma_f32_16x16x32_bf16 v[6:9], v[184:187], v[224:227], v[6:9]
	v_mfma_f32_16x16x32_bf16 v[2:5], v[192:195], v[224:227], v[2:5]
	v_mfma_f32_16x16x32_bf16 v[54:57], v[188:191], v[204:207], v[54:57]
	v_mfma_f32_16x16x32_bf16 v[50:53], v[196:199], v[204:207], v[50:53]
	v_mfma_f32_16x16x32_bf16 v[38:41], v[188:191], v[212:215], v[38:41]
	v_mfma_f32_16x16x32_bf16 v[34:37], v[196:199], v[212:215], v[34:37]
	v_mfma_f32_16x16x32_bf16 v[22:25], v[188:191], v[220:223], v[22:25]
	v_mfma_f32_16x16x32_bf16 v[18:21], v[196:199], v[220:223], v[18:21]
	v_mfma_f32_16x16x32_bf16 v[6:9], v[188:191], v[228:231], v[6:9]
	v_mfma_f32_16x16x32_bf16 v[2:5], v[196:199], v[228:231], v[2:5]
	s_setprio 0
	s_barrier
	s_add_i32 s79, s79, 2
	s_add_u32 s40, s40, 0x100
	s_addc_u32 s41, s41, 0
	s_add_u32 s67, s67, 0x100
	s_addc_u32 s78, s78, 0
	s_cmp_lt_u32 s79, 30
	s_cbranch_scc1 .LBB0_581
	s_andn2_b64 vcc, exec, s[24:25]
	s_cbranch_vccnz .LBB0_584
	s_barrier

; #define PG8_STAGE(bufoff, gbase, voff) do { _Pragma("unroll") for (int _i = 0; _i < 2; ++_i) \
;         __builtin_amdgcn_global_load_lds((const unsigned*)((const char*)(gbase) + (voff)[_i]), (PG8_LAS unsigned*)(lds + (bufoff) + ldsw + _i * 8192), 16, 0, 0); } while (0)
; #define PG8_LDA(dst, b, h) do { _Pragma("unroll") for (int m = 0; m < 4; ++m) _Pragma("unroll") for (int k = 0; k < 2; ++k) dst[m][k] = *(const PG8_LAS bf16x8*)(lds + PG8_SA(b, h) + aoff + m * 2048 + k * 1024); } while (0)
; #define PG8_LDB(dst, b, h) do { _Pragma("unroll") for (int n = 0; n < 2; ++n) _Pragma("unroll") for (int k = 0; k < 2; ++k) dst[n][k] = *(const PG8_LAS bf16x8*)(lds + PG8_SB(b, h) + boff + n * 2048 + k * 1024); } while (0)
; #define PG8_MMA(ai, bj, At, Bt) do { __builtin_amdgcn_s_setprio(1); _Pragma("unroll") for (int m = 0; m < 4; ++m) _Pragma("unroll") for (int n = 0; n < 2; ++n) _Pragma("unroll") for (int k = 0; k < 2; ++k) \
;         acc[ai][bj][m][n] = __builtin_amdgcn_mfma_f32_16x16x32_bf16(Bt[n][k], At[m][k], acc[ai][bj][m][n], 0, 0, 0); __builtin_amdgcn_s_setprio(0); } while (0)
; #define PG8_WAIT_V(n) asm volatile("s_waitcnt vmcnt(" #n ")" ::: "memory")
; #define PG8_WAIT_L(n) asm volatile("s_waitcnt lgkmcnt(" #n ")" ::: "memory")
; #define PG8_BAR __builtin_amdgcn_s_barrier()
; #define PG8_SCHED __builtin_amdgcn_sched_barrier(0)
; template <class Epi, class Sched, bool ALIGN_EPI = false, bool SP2 = false, bool KSEG = false>
; __device__ __forceinline__ void gemm_phase(PG8_LAS unsigned char* lds, const Gemm g, const Sched& S, const Epi& E) {
;     ...
;             PG8_LDB(B0, 0, 0); PG8_LDB(B1, 0, 1); PG8_SCHED; PG8_LDA(At, 0, 0); PG8_STAGE(PG8_SA(1, 1), a1 + hstep, voffA);
;             PG8_WAIT_V(8); PG8_WAIT_L(0); PG8_BAR; PG8_MMA(0, 0, At, B0); PG8_MMA(0, 1, At, B1); PG8_BAR; PG8_SCHED;
;             PG8_LDA(At, 0, 1); PG8_STAGE(PG8_SB(0, 0), b2, voffB); PG8_STAGE(PG8_SB(0, 1), b2 + hstep, voffB); PG8_STAGE(PG8_SA(0, 0), a2, voffA);
;             PG8_WAIT_V(8); PG8_WAIT_L(0); PG8_BAR; PG8_MMA(1, 0, At, B0); PG8_MMA(1, 1, At, B1); PG8_BAR; PG8_SCHED;
.LBB0_621:
	ds_read_b128 v[146:149], v1
	ds_read_b128 v[156:159], v1 offset:1024
	ds_read_b128 v[160:163], v1 offset:2048
	ds_read_b128 v[164:167], v1 offset:3072
	ds_read_b128 v[168:171], v153
	ds_read_b128 v[172:175], v153 offset:1024
	ds_read_b128 v[176:179], v153 offset:2048
	ds_read_b128 v[180:183], v153 offset:3072
	s_add_u32 s26, s24, 0xffea0080
	s_addc_u32 s27, s25, -1
	s_cmpk_eq_i32 s50, 0x54
	s_cselect_b32 s29, s21, s27
	s_cselect_b32 s28, s20, s26
	s_cselect_b32 s27, s9, s49
	s_cselect_b32 s26, s8, s48
	s_add_u32 s98, s24, 0xffea0000
	s_addc_u32 s99, s25, -1
	s_mov_b32 m0, s40
	v_lshl_add_u64 v[216:217], s[98:99], 0, v[140:141]
	global_load_lds_dwordx4 v[216:217], off
	s_mov_b32 m0, s41
	v_lshl_add_u64 v[216:217], s[98:99], 0, v[142:143]
	global_load_lds_dwordx4 v[216:217], off
	v_lshl_add_u64 v[216:217], s[24:25], 0, v[132:133]
	s_add_i32 m0, s31, 0xc000
	ds_read_b128 v[184:187], v154
	ds_read_b128 v[188:191], v154 offset:1024
	ds_read_b128 v[192:195], v154 offset:2048
	ds_read_b128 v[196:199], v154 offset:3072
	ds_read_b128 v[200:203], v154 offset:4096
	ds_read_b128 v[204:207], v154 offset:5120
	ds_read_b128 v[208:211], v154 offset:6144
	ds_read_b128 v[212:215], v154 offset:7168
	global_load_lds_dwordx4 v[216:217], off
	s_add_i32 m0, s31, 0xe000
	v_lshl_add_u64 v[216:217], s[24:25], 0, v[134:135]
	global_load_lds_dwordx4 v[216:217], off
	s_waitcnt vmcnt(8)
	s_waitcnt lgkmcnt(0)
	s_barrier
	s_setprio 1
	s_waitcnt lgkmcnt(0)
	v_mfma_f32_16x16x32_bf16 v[126:129], v[146:149], v[184:187], v[126:129]
	v_mfma_f32_16x16x32_bf16 v[122:125], v[160:163], v[184:187], v[122:125]
	v_mfma_f32_16x16x32_bf16 v[110:113], v[146:149], v[192:195], v[110:113]
	v_mfma_f32_16x16x32_bf16 v[106:109], v[160:163], v[192:195], v[106:109]
	v_mfma_f32_16x16x32_bf16 v[94:97], v[146:149], v[200:203], v[94:97]
	v_mfma_f32_16x16x32_bf16 v[90:93], v[160:163], v[200:203], v[90:93]
	v_mfma_f32_16x16x32_bf16 v[78:81], v[146:149], v[208:211], v[78:81]
	v_mfma_f32_16x16x32_bf16 v[74:77], v[160:163], v[208:211], v[74:77]
	v_mfma_f32_16x16x32_bf16 v[126:129], v[156:159], v[188:191], v[126:129]
	v_mfma_f32_16x16x32_bf16 v[122:125], v[164:167], v[188:191], v[122:125]
	v_mfma_f32_16x16x32_bf16 v[110:113], v[156:159], v[196:199], v[110:113]
	v_mfma_f32_16x16x32_bf16 v[106:109], v[164:167], v[196:199], v[106:109]
	v_mfma_f32_16x16x32_bf16 v[94:97], v[156:159], v[204:207], v[94:97]
	v_mfma_f32_16x16x32_bf16 v[90:93], v[164:167], v[204:207], v[90:93]
	v_mfma_f32_16x16x32_bf16 v[78:81], v[156:159], v[212:215], v[78:81]
	v_mfma_f32_16x16x32_bf16 v[74:77], v[164:167], v[212:215], v[74:77]
	s_setprio 0
	s_setprio 1
	v_mfma_f32_16x16x32_bf16 v[118:121], v[168:171], v[184:187], v[118:121]
	v_mfma_f32_16x16x32_bf16 v[114:117], v[176:179], v[184:187], v[114:117]
	v_mfma_f32_16x16x32_bf16 v[102:105], v[168:171], v[192:195], v[102:105]
	v_mfma_f32_16x16x32_bf16 v[98:101], v[176:179], v[192:195], v[98:101]
	v_mfma_f32_16x16x32_bf16 v[86:89], v[168:171], v[200:203], v[86:89]
	v_mfma_f32_16x16x32_bf16 v[82:85], v[176:179], v[200:203], v[82:85]
	v_mfma_f32_16x16x32_bf16 v[70:73], v[168:171], v[208:211], v[70:73]
	v_mfma_f32_16x16x32_bf16 v[66:69], v[176:179], v[208:211], v[66:69]
	v_mfma_f32_16x16x32_bf16 v[118:121], v[172:175], v[188:191], v[118:121]
	v_mfma_f32_16x16x32_bf16 v[114:117], v[180:183], v[188:191], v[114:117]
	v_mfma_f32_16x16x32_bf16 v[102:105], v[172:175], v[196:199], v[102:105]
	v_mfma_f32_16x16x32_bf16 v[98:101], v[180:183], v[196:199], v[98:101]
	v_mfma_f32_16x16x32_bf16 v[86:89], v[172:175], v[204:207], v[86:89]
	v_mfma_f32_16x16x32_bf16 v[82:85], v[180:183], v[204:207], v[82:85]
	v_mfma_f32_16x16x32_bf16 v[70:73], v[172:175], v[212:215], v[70:73]
	v_mfma_f32_16x16x32_bf16 v[66:69], v[180:183], v[212:215], v[66:69]
	s_setprio 0
	s_barrier
	s_add_i32 s33, s42, s30
	v_lshl_add_u64 v[216:217], s[26:27], 0, v[130:131]
	s_mov_b32 m0, s33
	ds_read_b128 v[184:187], v154 offset:16384
	ds_read_b128 v[188:191], v154 offset:17408
	ds_read_b128 v[192:195], v154 offset:18432
	ds_read_b128 v[196:199], v154 offset:19456
	ds_read_b128 v[200:203], v154 offset:20480
	ds_read_b128 v[204:207], v154 offset:21504
	ds_read_b128 v[208:211], v154 offset:22528
	ds_read_b128 v[212:215], v154 offset:23552
	global_load_lds_dwordx4 v[216:217], off
	s_add_i32 m0, s33, 0x2000
	s_add_u32 s54, s26, 0x160000
	v_lshl_add_u64 v[218:219], s[26:27], 0, v[144:145]
	s_addc_u32 s55, s27, 0
	s_add_i32 s33, s43, s30
	global_load_lds_dwordx4 v[218:219], off
	s_mov_b32 m0, s33
	v_lshl_add_u64 v[220:221], s[54:55], 0, v[130:131]
	global_load_lds_dwordx4 v[220:221], off
	s_add_i32 m0, s33, 0x2000
	v_lshl_add_u64 v[220:221], s[54:55], 0, v[144:145]
	global_load_lds_dwordx4 v[220:221], off
	s_waitcnt vmcnt(6)
	s_waitcnt lgkmcnt(0)
	s_barrier
; #define PG8_STAGE(bufoff, gbase, voff) do { _Pragma("unroll") for (int _i = 0; _i < 2; ++_i) \
;         __builtin_amdgcn_global_load_lds((const unsigned*)((const char*)(gbase) + (voff)[_i]), (PG8_LAS unsigned*)(lds + (bufoff) + ldsw + _i * 8192), 16, 0, 0); } while (0)
; #define PG8_LDA(dst, b, h) do { _Pragma("unroll") for (int m = 0; m < 4; ++m) _Pragma("unroll") for (int k = 0; k < 2; ++k) dst[m][k] = *(const PG8_LAS bf16x8*)(lds + PG8_SA(b, h) + aoff + m * 2048 + k * 1024); } while (0)
; #define PG8_LDB(dst, b, h) do { _Pragma("unroll") for (int n = 0; n < 2; ++n) _Pragma("unroll") for (int k = 0; k < 2; ++k) dst[n][k] = *(const PG8_LAS bf16x8*)(lds + PG8_SB(b, h) + boff + n * 2048 + k * 1024); } while (0)
; #define PG8_MMA(ai, bj, At, Bt) do { __builtin_amdgcn_s_setprio(1); _Pragma("unroll") for (int m = 0; m < 4; ++m) _Pragma("unroll") for (int n = 0; n < 2; ++n) _Pragma("unroll") for (int k = 0; k < 2; ++k) \
;         acc[ai][bj][m][n] = __builtin_amdgcn_mfma_f32_16x16x32_bf16(Bt[n][k], At[m][k], acc[ai][bj][m][n], 0, 0, 0); __builtin_amdgcn_s_setprio(0); } while (0)
; #define PG8_WAIT_V(n) asm volatile("s_waitcnt vmcnt(" #n ")" ::: "memory")
; #define PG8_WAIT_L(n) asm volatile("s_waitcnt lgkmcnt(" #n ")" ::: "memory")
; #define PG8_BAR __builtin_amdgcn_s_barrier()
; #define PG8_SCHED __builtin_amdgcn_sched_barrier(0)
; template <class Epi, class Sched, bool ALIGN_EPI = false, bool SP2 = false, bool KSEG = false>
; __device__ __forceinline__ void gemm_phase(PG8_LAS unsigned char* lds, const Gemm g, const Sched& S, const Epi& E) {
;     ...
;             PG8_WAIT_V(8); PG8_WAIT_L(0); PG8_BAR; PG8_MMA(1, 0, At, B0); PG8_MMA(1, 1, At, B1); PG8_BAR; PG8_SCHED;
;             PG8_LDB(B0, 1, 0); PG8_LDB(B1, 1, 1); PG8_SCHED; PG8_LDA(At, 1, 0); PG8_STAGE(PG8_SA(0, 1), a2 + hstep, voffA);
;             PG8_WAIT_V(8); PG8_WAIT_L(0); PG8_BAR; PG8_MMA(0, 0, At, B0); PG8_MMA(0, 1, At, B1); PG8_BAR; PG8_SCHED;
	s_setprio 1
	s_waitcnt lgkmcnt(0)
	v_mfma_f32_16x16x32_bf16 v[62:65], v[146:149], v[184:187], v[62:65]
	v_mfma_f32_16x16x32_bf16 v[58:61], v[160:163], v[184:187], v[58:61]
	v_mfma_f32_16x16x32_bf16 v[46:49], v[146:149], v[192:195], v[46:49]
	v_mfma_f32_16x16x32_bf16 v[42:45], v[160:163], v[192:195], v[42:45]
	v_mfma_f32_16x16x32_bf16 v[30:33], v[146:149], v[200:203], v[30:33]
	v_mfma_f32_16x16x32_bf16 v[26:29], v[160:163], v[200:203], v[26:29]
	v_mfma_f32_16x16x32_bf16 v[14:17], v[146:149], v[208:211], v[14:17]
	v_mfma_f32_16x16x32_bf16 v[10:13], v[160:163], v[208:211], v[10:13]
	v_mfma_f32_16x16x32_bf16 v[62:65], v[156:159], v[188:191], v[62:65]
	v_mfma_f32_16x16x32_bf16 v[58:61], v[164:167], v[188:191], v[58:61]
	v_mfma_f32_16x16x32_bf16 v[46:49], v[156:159], v[196:199], v[46:49]
	v_mfma_f32_16x16x32_bf16 v[42:45], v[164:167], v[196:199], v[42:45]
	v_mfma_f32_16x16x32_bf16 v[30:33], v[156:159], v[204:207], v[30:33]
	v_mfma_f32_16x16x32_bf16 v[26:29], v[164:167], v[204:207], v[26:29]
	v_mfma_f32_16x16x32_bf16 v[14:17], v[156:159], v[212:215], v[14:17]
	v_mfma_f32_16x16x32_bf16 v[10:13], v[164:167], v[212:215], v[10:13]
	s_setprio 0
	s_setprio 1
	v_mfma_f32_16x16x32_bf16 v[54:57], v[168:171], v[184:187], v[54:57]
	v_mfma_f32_16x16x32_bf16 v[50:53], v[176:179], v[184:187], v[50:53]
	v_mfma_f32_16x16x32_bf16 v[38:41], v[168:171], v[192:195], v[38:41]
	v_mfma_f32_16x16x32_bf16 v[34:37], v[176:179], v[192:195], v[34:37]
	v_mfma_f32_16x16x32_bf16 v[22:25], v[168:171], v[200:203], v[22:25]
	v_mfma_f32_16x16x32_bf16 v[18:21], v[176:179], v[200:203], v[18:21]
	v_mfma_f32_16x16x32_bf16 v[6:9], v[168:171], v[208:211], v[6:9]
	v_mfma_f32_16x16x32_bf16 v[2:5], v[176:179], v[208:211], v[2:5]
	v_mfma_f32_16x16x32_bf16 v[54:57], v[172:175], v[188:191], v[54:57]
	v_mfma_f32_16x16x32_bf16 v[50:53], v[180:183], v[188:191], v[50:53]
	v_mfma_f32_16x16x32_bf16 v[38:41], v[172:175], v[196:199], v[38:41]
	v_mfma_f32_16x16x32_bf16 v[34:37], v[180:183], v[196:199], v[34:37]
	v_mfma_f32_16x16x32_bf16 v[22:25], v[172:175], v[204:207], v[22:25]
	v_mfma_f32_16x16x32_bf16 v[18:21], v[180:183], v[204:207], v[18:21]
	v_mfma_f32_16x16x32_bf16 v[6:9], v[172:175], v[212:215], v[6:9]
	v_mfma_f32_16x16x32_bf16 v[2:5], v[180:183], v[212:215], v[2:5]
	s_setprio 0
	s_barrier
	s_add_i32 s33, 0, 0x18000
	v_add_u32_e32 v155, s33, v150
	s_add_i32 s53, 0, 0x1c000
	ds_read_b128 v[146:149], v155
	ds_read_b128 v[156:159], v155 offset:1024
	ds_read_b128 v[160:163], v155 offset:2048
	ds_read_b128 v[164:167], v155 offset:3072
	v_add_u32_e32 v155, s53, v150
	ds_read_b128 v[168:171], v155
	ds_read_b128 v[172:175], v155 offset:1024
	ds_read_b128 v[176:179], v155 offset:2048
	ds_read_b128 v[180:183], v155 offset:3072
	s_mov_b32 m0, s31
	v_lshl_add_u64 v[224:225], s[28:29], 0, v[140:141]
	global_load_lds_dwordx4 v[224:225], off
	s_mov_b32 m0, s36
	v_lshl_add_u64 v[224:225], s[28:29], 0, v[142:143]
	global_load_lds_dwordx4 v[224:225], off
	s_add_u32 s28, s28, 0x160000
	s_addc_u32 s29, s29, 0
	s_mov_b32 m0, s37
	v_lshl_add_u64 v[224:225], s[28:29], 0, v[140:141]
	ds_read_b128 v[184:187], v154 offset:32768
	ds_read_b128 v[188:191], v154 offset:33792
	ds_read_b128 v[192:195], v154 offset:34816
	ds_read_b128 v[196:199], v154 offset:35840
	ds_read_b128 v[200:203], v154 offset:36864
	ds_read_b128 v[204:207], v154 offset:37888
	ds_read_b128 v[208:211], v154 offset:38912
	ds_read_b128 v[212:215], v154 offset:39936
	global_load_lds_dwordx4 v[224:225], off
	s_mov_b32 m0, s38
	v_lshl_add_u64 v[224:225], s[28:29], 0, v[142:143]
	global_load_lds_dwordx4 v[224:225], off
	s_waitcnt vmcnt(8)
	s_waitcnt lgkmcnt(0)
	s_barrier
; #define PG8_STAGE(bufoff, gbase, voff) do { _Pragma("unroll") for (int _i = 0; _i < 2; ++_i) \
;         __builtin_amdgcn_global_load_lds((const unsigned*)((const char*)(gbase) + (voff)[_i]), (PG8_LAS unsigned*)(lds + (bufoff) + ldsw + _i * 8192), 16, 0, 0); } while (0)
; #define PG8_LDA(dst, b, h) do { _Pragma("unroll") for (int m = 0; m < 4; ++m) _Pragma("unroll") for (int k = 0; k < 2; ++k) dst[m][k] = *(const PG8_LAS bf16x8*)(lds + PG8_SA(b, h) + aoff + m * 2048 + k * 1024); } while (0)
; #define PG8_MMA(ai, bj, At, Bt) do { __builtin_amdgcn_s_setprio(1); _Pragma("unroll") for (int m = 0; m < 4; ++m) _Pragma("unroll") for (int n = 0; n < 2; ++n) _Pragma("unroll") for (int k = 0; k < 2; ++k) \
;         acc[ai][bj][m][n] = __builtin_amdgcn_mfma_f32_16x16x32_bf16(Bt[n][k], At[m][k], acc[ai][bj][m][n], 0, 0, 0); __builtin_amdgcn_s_setprio(0); } while (0)
; #define PG8_WAIT_V(n) asm volatile("s_waitcnt vmcnt(" #n ")" ::: "memory")
; #define PG8_WAIT_L(n) asm volatile("s_waitcnt lgkmcnt(" #n ")" ::: "memory")
; #define PG8_BAR __builtin_amdgcn_s_barrier()
; #define PG8_SCHED __builtin_amdgcn_sched_barrier(0)
; template <class Epi, class Sched, bool ALIGN_EPI = false, bool SP2 = false, bool KSEG = false>
; __device__ __forceinline__ void gemm_phase(PG8_LAS unsigned char* lds, const Gemm g, const Sched& S, const Epi& E) {
;     ...
;             PG8_WAIT_V(8); PG8_WAIT_L(0); PG8_BAR; PG8_MMA(0, 0, At, B0); PG8_MMA(0, 1, At, B1); PG8_BAR; PG8_SCHED;
;             PG8_LDA(At, 1, 1); PG8_STAGE(PG8_SB(1, 0), b3, voffB); PG8_STAGE(PG8_SB(1, 1), b3 + hstep, voffB); PG8_STAGE(PG8_SA(1, 0), a3, voffA);
;             PG8_WAIT_V(8); PG8_WAIT_L(0); PG8_BAR; PG8_MMA(1, 0, At, B0); PG8_MMA(1, 1, At, B1); PG8_BAR; PG8_SCHED;
	s_setprio 1
	s_waitcnt lgkmcnt(0)
	v_mfma_f32_16x16x32_bf16 v[126:129], v[146:149], v[184:187], v[126:129]
	v_mfma_f32_16x16x32_bf16 v[122:125], v[160:163], v[184:187], v[122:125]
	v_mfma_f32_16x16x32_bf16 v[110:113], v[146:149], v[192:195], v[110:113]
	v_mfma_f32_16x16x32_bf16 v[106:109], v[160:163], v[192:195], v[106:109]
	v_mfma_f32_16x16x32_bf16 v[94:97], v[146:149], v[200:203], v[94:97]
	v_mfma_f32_16x16x32_bf16 v[90:93], v[160:163], v[200:203], v[90:93]
	v_mfma_f32_16x16x32_bf16 v[78:81], v[146:149], v[208:211], v[78:81]
	v_mfma_f32_16x16x32_bf16 v[74:77], v[160:163], v[208:211], v[74:77]
	v_mfma_f32_16x16x32_bf16 v[126:129], v[156:159], v[188:191], v[126:129]
	v_mfma_f32_16x16x32_bf16 v[122:125], v[164:167], v[188:191], v[122:125]
	v_mfma_f32_16x16x32_bf16 v[110:113], v[156:159], v[196:199], v[110:113]
	v_mfma_f32_16x16x32_bf16 v[106:109], v[164:167], v[196:199], v[106:109]
	v_mfma_f32_16x16x32_bf16 v[94:97], v[156:159], v[204:207], v[94:97]
	v_mfma_f32_16x16x32_bf16 v[90:93], v[164:167], v[204:207], v[90:93]
	v_mfma_f32_16x16x32_bf16 v[78:81], v[156:159], v[212:215], v[78:81]
	v_mfma_f32_16x16x32_bf16 v[74:77], v[164:167], v[212:215], v[74:77]
	s_setprio 0
	s_setprio 1
	v_mfma_f32_16x16x32_bf16 v[118:121], v[168:171], v[184:187], v[118:121]
	v_mfma_f32_16x16x32_bf16 v[114:117], v[176:179], v[184:187], v[114:117]
	v_mfma_f32_16x16x32_bf16 v[102:105], v[168:171], v[192:195], v[102:105]
	v_mfma_f32_16x16x32_bf16 v[98:101], v[176:179], v[192:195], v[98:101]
	v_mfma_f32_16x16x32_bf16 v[86:89], v[168:171], v[200:203], v[86:89]
	v_mfma_f32_16x16x32_bf16 v[82:85], v[176:179], v[200:203], v[82:85]
	v_mfma_f32_16x16x32_bf16 v[70:73], v[168:171], v[208:211], v[70:73]
	v_mfma_f32_16x16x32_bf16 v[66:69], v[176:179], v[208:211], v[66:69]
	v_mfma_f32_16x16x32_bf16 v[118:121], v[172:175], v[188:191], v[118:121]
	v_mfma_f32_16x16x32_bf16 v[114:117], v[180:183], v[188:191], v[114:117]
	v_mfma_f32_16x16x32_bf16 v[102:105], v[172:175], v[196:199], v[102:105]
	v_mfma_f32_16x16x32_bf16 v[98:101], v[180:183], v[196:199], v[98:101]
	v_mfma_f32_16x16x32_bf16 v[86:89], v[172:175], v[204:207], v[86:89]
	v_mfma_f32_16x16x32_bf16 v[82:85], v[180:183], v[204:207], v[82:85]
	v_mfma_f32_16x16x32_bf16 v[70:73], v[172:175], v[212:215], v[70:73]
	v_mfma_f32_16x16x32_bf16 v[66:69], v[180:183], v[212:215], v[66:69]
	s_setprio 0
	s_barrier
	s_add_i32 s28, s33, s30
	v_lshl_add_u64 v[216:217], v[216:217], 0, s[12:13]
	s_mov_b32 m0, s28
	ds_read_b128 v[184:187], v154 offset:49152
	ds_read_b128 v[188:191], v154 offset:50176
	ds_read_b128 v[192:195], v154 offset:51200
	ds_read_b128 v[196:199], v154 offset:52224
	ds_read_b128 v[200:203], v154 offset:53248
	ds_read_b128 v[204:207], v154 offset:54272
	ds_read_b128 v[208:211], v154 offset:55296
	ds_read_b128 v[212:215], v154 offset:56320
	global_load_lds_dwordx4 v[216:217], off
	s_add_i32 m0, s28, 0x2000
	s_add_u32 s26, s26, 0x160080
	v_lshl_add_u64 v[216:217], v[218:219], 0, s[12:13]
	s_addc_u32 s27, s27, 0
	s_add_i32 s28, s53, s30
	global_load_lds_dwordx4 v[216:217], off
	s_mov_b32 m0, s28
	v_lshl_add_u64 v[216:217], s[26:27], 0, v[130:131]
	global_load_lds_dwordx4 v[216:217], off
	s_add_i32 m0, s28, 0x2000
	v_lshl_add_u64 v[216:217], s[26:27], 0, v[144:145]
	global_load_lds_dwordx4 v[216:217], off
	s_waitcnt vmcnt(6)
	s_waitcnt lgkmcnt(0)
	s_barrier
	s_setprio 1
	s_waitcnt lgkmcnt(0)
	v_mfma_f32_16x16x32_bf16 v[62:65], v[146:149], v[184:187], v[62:65]
	v_mfma_f32_16x16x32_bf16 v[58:61], v[160:163], v[184:187], v[58:61]
	v_mfma_f32_16x16x32_bf16 v[46:49], v[146:149], v[192:195], v[46:49]
	v_mfma_f32_16x16x32_bf16 v[42:45], v[160:163], v[192:195], v[42:45]
	v_mfma_f32_16x16x32_bf16 v[30:33], v[146:149], v[200:203], v[30:33]
	v_mfma_f32_16x16x32_bf16 v[26:29], v[160:163], v[200:203], v[26:29]
	v_mfma_f32_16x16x32_bf16 v[14:17], v[146:149], v[208:211], v[14:17]
	v_mfma_f32_16x16x32_bf16 v[10:13], v[160:163], v[208:211], v[10:13]
	v_mfma_f32_16x16x32_bf16 v[62:65], v[156:159], v[188:191], v[62:65]
	v_mfma_f32_16x16x32_bf16 v[58:61], v[164:167], v[188:191], v[58:61]
	v_mfma_f32_16x16x32_bf16 v[46:49], v[156:159], v[196:199], v[46:49]
	v_mfma_f32_16x16x32_bf16 v[42:45], v[164:167], v[196:199], v[42:45]
	v_mfma_f32_16x16x32_bf16 v[30:33], v[156:159], v[204:207], v[30:33]
	v_mfma_f32_16x16x32_bf16 v[26:29], v[164:167], v[204:207], v[26:29]
	v_mfma_f32_16x16x32_bf16 v[14:17], v[156:159], v[212:215], v[14:17]
	v_mfma_f32_16x16x32_bf16 v[10:13], v[164:167], v[212:215], v[10:13]
	s_setprio 0
	s_setprio 1
	v_mfma_f32_16x16x32_bf16 v[54:57], v[168:171], v[184:187], v[54:57]
	v_mfma_f32_16x16x32_bf16 v[50:53], v[176:179], v[184:187], v[50:53]
	v_mfma_f32_16x16x32_bf16 v[38:41], v[168:171], v[192:195], v[38:41]
	v_mfma_f32_16x16x32_bf16 v[34:37], v[176:179], v[192:195], v[34:37]
	v_mfma_f32_16x16x32_bf16 v[22:25], v[168:171], v[200:203], v[22:25]
	v_mfma_f32_16x16x32_bf16 v[18:21], v[176:179], v[200:203], v[18:21]
	v_mfma_f32_16x16x32_bf16 v[6:9], v[168:171], v[208:211], v[6:9]
	v_mfma_f32_16x16x32_bf16 v[2:5], v[176:179], v[208:211], v[2:5]
	v_mfma_f32_16x16x32_bf16 v[54:57], v[172:175], v[188:191], v[54:57]
	v_mfma_f32_16x16x32_bf16 v[50:53], v[180:183], v[188:191], v[50:53]
	v_mfma_f32_16x16x32_bf16 v[38:41], v[172:175], v[196:199], v[38:41]
	v_mfma_f32_16x16x32_bf16 v[34:37], v[180:183], v[196:199], v[34:37]
	v_mfma_f32_16x16x32_bf16 v[22:25], v[172:175], v[204:207], v[22:25]
	v_mfma_f32_16x16x32_bf16 v[18:21], v[180:183], v[204:207], v[18:21]
	v_mfma_f32_16x16x32_bf16 v[6:9], v[172:175], v[212:215], v[6:9]
	v_mfma_f32_16x16x32_bf16 v[2:5], v[180:183], v[212:215], v[2:5]
	s_setprio 0
	s_barrier
	s_add_i32 s50, s50, 2
	s_add_u32 s24, s24, 0x100
	s_addc_u32 s25, s25, 0
	s_add_u32 s48, s48, 0x100
	s_addc_u32 s49, s49, 0
	s_cmpk_lt_u32 s50, 0x56
	s_cbranch_scc1 .LBB0_621
	s_andn2_b64 vcc, exec, s[18:19]
	s_cbranch_vccnz .LBB0_624
	s_barrier
